# attention: exact-zero skip threshold 128 log2 units (v_exp_f32 verified to return +0 below 2^-127 on this chip), item table re-dealt with 3-5 items per workgroup
# baseline (speedup 1.0000x reference)
.Ltbl:
	s_and_b32 s0, s73, 15
	s_mov_b32 s100, 0x40002b7c
	s_cmp_eq_u32 s0, 1
	s_cselect_b32 s100, 0x8731c7a5, s100
	s_cmp_eq_u32 s0, 2
	s_cselect_b32 s100, 0x403e06bb, s100
	s_cmp_eq_u32 s0, 3
	s_cselect_b32 s100, 0x399ae, s100
	s_cmp_eq_u32 s0, 4
	s_cselect_b32 s100, 0x14abe, s100
	s_cmp_eq_u32 s0, 5
	s_cselect_b32 s100, 0x40169cab, s100
	s_cmp_eq_u32 s0, 6
	s_cselect_b32 s100, 0x40221776, s100
	s_cmp_eq_u32 s0, 7
	s_cselect_b32 s100, 0x843996ef, s100
	s_cmp_eq_u32 s0, 8
	s_cselect_b32 s100, 0x836125b3, s100
	s_cmp_eq_u32 s0, 9
	s_cselect_b32 s100, 0x1193d, s100
	s_cmp_eq_u32 s0, 10
	s_cselect_b32 s100, 0x89290574, s100
	s_cmp_eq_u32 s0, 11
	s_cselect_b32 s100, 0x308f5, s100
	s_cmp_eq_u32 s0, 12
	s_cselect_b32 s100, 0x28c7f, s100
	s_cmp_eq_u32 s0, 13
	s_cselect_b32 s100, 0x38eac, s100
	s_cmp_eq_u32 s0, 14
	s_cselect_b32 s100, 0x864d78a7, s100
	s_cmp_eq_u32 s0, 15
	s_cselect_b32 s100, 0x8134b7f7, s100
	s_mov_b32 s74, 0

.LBB0_737:
	v_mov_b32_e32 v130, v210
	s_add_i32 s74, s74, 1
	v_ashrrev_i32_e32 v189, 31, v188
	v_lshl_add_u64 v[128:129], v[188:189], 0, s[46:47]
	v_lshlrev_b32_e32 v130, 2, v130
	v_lshlrev_b64 v[140:141], 11, v[128:129]
	v_lshl_or_b32 v140, s75, 1, v140
	v_ashrrev_i32_e32 v131, 31, v130
	v_lshl_add_u64 v[128:129], s[48:49], 0, v[140:141]
	v_lshlrev_b64 v[136:137], 1, v[130:131]
	v_lshl_add_u64 v[134:135], v[128:129], 0, v[136:137]
	v_lshlrev_b32_e32 v215, 3, v206
	global_load_dwordx2 v[204:205], v215, s[52:53]
	global_load_dwordx2 v[160:161], v[134:135], off
	global_load_dwordx2 v[162:163], v[134:135], off offset:16
	global_load_dwordx2 v[164:165], v[134:135], off offset:32
	global_load_dwordx2 v[166:167], v[134:135], off offset:48
	global_load_dwordx2 v[168:169], v[134:135], off offset:64
	global_load_dwordx2 v[170:171], v[134:135], off offset:80
	global_load_dwordx2 v[172:173], v[134:135], off offset:96
	global_load_dwordx2 v[174:175], v[134:135], off offset:112
	global_load_dwordx2 v[202:203], v[134:135], off offset:128
	global_load_dwordx2 v[244:245], v[134:135], off offset:160
	global_load_dwordx2 v[246:247], v[134:135], off offset:176
	global_load_dwordx2 v[248:249], v[134:135], off offset:192
	global_load_dwordx2 v[250:251], v[134:135], off offset:208
	global_load_dwordx2 v[252:253], v[134:135], off offset:224
	global_load_dwordx2 v[254:255], v[134:135], off offset:240
	s_lshr_b32 s0, s87, 2
	s_add_i32 s0, s0, 0x8000
	v_add_u32_e32 v217, s0, v215
	v_lshl_add_u32 v219, v210, 4, s0
	s_waitcnt lgkmcnt(0)
	s_barrier
	s_waitcnt vmcnt(15)
	ds_write_b64 v217, v[204:205]
	global_load_dwordx2 v[204:205], v[134:135], off offset:144
	s_lshr_b32 s0, s100, 30
	s_add_i32 s0, s0, 3
	s_cmp_lt_u32 s74, s0
	s_cbranch_scc1 .Lpf_do
	s_waitcnt vmcnt(0)
	s_branch .Lpf_done

.Lpf_done:
	v_mov_b32_e32 v128, v197
	v_mov_b32_e32 v129, v196
	s_nop 0
	v_permlane32_swap_b32_e32 v197, v128
	v_permlane32_swap_b32_e32 v196, v129
	v_add_f32_e32 v148, v197, v128
	v_add_f32_e32 v149, v196, v129
	v_div_scale_f32 v150, s[0:1], v148, v148, 1.0
	v_div_scale_f32 v152, s[0:1], v149, v149, -v208
	v_rcp_f32_e32 v154, v150
	v_rcp_f32_e32 v155, v152
	v_div_scale_f32 v151, vcc, 1.0, v148, 1.0
	v_fma_f32 v156, -v150, v154, 1.0
	v_fma_f32 v157, -v152, v155, 1.0
	v_fmac_f32_e32 v154, v156, v154
	v_div_scale_f32 v153, s[36:37], -v208, v149, -v208
	v_fmac_f32_e32 v155, v157, v155
	v_mul_f32_e32 v156, v151, v154
	v_mul_f32_e32 v157, v153, v155
	v_fma_f32 v158, -v150, v156, v151
	v_fma_f32 v159, -v152, v157, v153
	v_fmac_f32_e32 v156, v158, v154
	v_fmac_f32_e32 v157, v159, v155
	v_fma_f32 v150, -v150, v156, v151
	v_fma_f32 v151, -v152, v157, v153
	v_div_fmas_f32 v150, v150, v154, v156
	s_mov_b64 vcc, s[36:37]
	v_div_fixup_f32 v148, v150, v148, 1.0
	v_div_fmas_f32 v150, v151, v155, v157
	v_div_fixup_f32 v150, v150, v149, -v208
	v_pk_mul_f32 v[96:97], v[96:97], v[150:151] op_sel_hi:[1,0]
	v_pk_mul_f32 v[98:99], v[98:99], v[150:151] op_sel_hi:[1,0]
	v_pk_fma_f32 v[112:113], v[112:113], v[148:149], v[96:97] op_sel_hi:[1,0,1]
	v_pk_fma_f32 v[114:115], v[114:115], v[148:149], v[98:99] op_sel_hi:[1,0,1]
	v_mul_f32_e32 v96, v113, v113
	v_pk_fma_f32 v[96:97], v[112:113], v[112:113], v[96:97] op_sel_hi:[1,1,0]
	v_pk_mul_f32 v[100:101], v[100:101], v[150:151] op_sel_hi:[1,0]
	v_mul_f32_e32 v98, v115, v115
	v_pk_fma_f32 v[96:97], v[114:115], v[114:115], v[96:97]
	v_pk_fma_f32 v[100:101], v[116:117], v[148:149], v[100:101] op_sel_hi:[1,0,1]
	v_pk_add_f32 v[96:97], v[98:99], v[96:97] op_sel_hi:[0,1]
	v_pk_mul_f32 v[102:103], v[102:103], v[150:151] op_sel_hi:[1,0]
	v_mul_f32_e32 v116, v101, v101
	v_pk_fma_f32 v[96:97], v[100:101], v[100:101], v[96:97]
	v_pk_fma_f32 v[102:103], v[118:119], v[148:149], v[102:103] op_sel_hi:[1,0,1]
	v_pk_add_f32 v[96:97], v[116:117], v[96:97] op_sel_hi:[0,1]
	v_pk_mul_f32 v[104:105], v[104:105], v[150:151] op_sel_hi:[1,0]
	v_mul_f32_e32 v118, v103, v103
	v_pk_fma_f32 v[96:97], v[102:103], v[102:103], v[96:97]
	v_pk_fma_f32 v[104:105], v[120:121], v[148:149], v[104:105] op_sel_hi:[1,0,1]
	v_pk_add_f32 v[96:97], v[118:119], v[96:97] op_sel_hi:[0,1]
	v_pk_mul_f32 v[106:107], v[106:107], v[150:151] op_sel_hi:[1,0]
	v_mul_f32_e32 v120, v105, v105
	v_pk_fma_f32 v[96:97], v[104:105], v[104:105], v[96:97]
	v_pk_fma_f32 v[106:107], v[122:123], v[148:149], v[106:107] op_sel_hi:[1,0,1]
	v_pk_add_f32 v[96:97], v[120:121], v[96:97] op_sel_hi:[0,1]
	v_pk_mul_f32 v[108:109], v[108:109], v[150:151] op_sel_hi:[1,0]
	v_mul_f32_e32 v122, v107, v107
	v_pk_fma_f32 v[96:97], v[106:107], v[106:107], v[96:97]
	v_pk_fma_f32 v[108:109], v[124:125], v[148:149], v[108:109] op_sel_hi:[1,0,1]
	v_pk_add_f32 v[96:97], v[122:123], v[96:97] op_sel_hi:[0,1]
	v_pk_mul_f32 v[110:111], v[110:111], v[150:151] op_sel_hi:[1,0]
	v_pk_fma_f32 v[96:97], v[108:109], v[108:109], v[96:97]
	v_mul_f32_e32 v98, v109, v109
	v_pk_fma_f32 v[110:111], v[126:127], v[148:149], v[110:111] op_sel_hi:[1,0,1]
	v_pk_add_f32 v[96:97], v[98:99], v[96:97] op_sel_hi:[0,1]
	v_pk_fma_f32 v[96:97], v[110:111], v[110:111], v[96:97]
	v_mul_f32_e32 v98, v111, v111
	v_pk_mul_f32 v[82:83], v[82:83], v[150:151] op_sel_hi:[1,0]
	v_pk_add_f32 v[118:119], v[98:99], v[96:97] op_sel_hi:[0,1]
	v_pk_fma_f32 v[96:97], v[66:67], v[148:149], v[82:83] op_sel_hi:[1,0,1]
	v_pk_mul_f32 v[66:67], v[80:81], v[150:151] op_sel_hi:[1,0]
	v_lshl_add_u64 v[132:133], v[130:131], 2, s[52:53]
	v_pk_fma_f32 v[98:99], v[64:65], v[148:149], v[66:67] op_sel_hi:[1,0,1]
	v_pk_fma_f32 v[64:65], v[98:99], v[98:99], v[118:119]
	v_mul_f32_e32 v66, v99, v99
	ds_read_b128 v[128:131], v219
	v_pk_add_f32 v[64:65], v[66:67], v[64:65] op_sel_hi:[0,1]
	v_pk_fma_f32 v[64:65], v[96:97], v[96:97], v[64:65]
	v_mul_f32_e32 v66, v97, v97
	v_pk_add_f32 v[64:65], v[66:67], v[64:65] op_sel_hi:[0,1]
	v_pk_mul_f32 v[66:67], v[86:87], v[150:151] op_sel_hi:[1,0]
	v_pk_mul_f32 v[50:51], v[50:51], v[150:151] op_sel_hi:[1,0]
	v_pk_fma_f32 v[80:81], v[70:71], v[148:149], v[66:67] op_sel_hi:[1,0,1]
	v_pk_mul_f32 v[66:67], v[84:85], v[150:151] op_sel_hi:[1,0]
	v_pk_mul_f32 v[18:19], v[18:19], v[150:151] op_sel_hi:[1,0]
	v_pk_fma_f32 v[82:83], v[68:69], v[148:149], v[66:67] op_sel_hi:[1,0,1]
	s_mov_b32 s0, 0x800000
	v_pk_fma_f32 v[64:65], v[82:83], v[82:83], v[64:65]
	v_mul_f32_e32 v66, v83, v83
	v_pk_add_f32 v[64:65], v[66:67], v[64:65] op_sel_hi:[0,1]
	v_pk_fma_f32 v[64:65], v[80:81], v[80:81], v[64:65]
	v_mul_f32_e32 v66, v81, v81
	v_pk_add_f32 v[64:65], v[66:67], v[64:65] op_sel_hi:[0,1]
	v_pk_mul_f32 v[66:67], v[90:91], v[150:151] op_sel_hi:[1,0]
	v_lshl_add_u64 v[140:141], s[68:69], 0, v[140:141]
	v_pk_fma_f32 v[74:75], v[74:75], v[148:149], v[66:67] op_sel_hi:[1,0,1]
	v_pk_mul_f32 v[66:67], v[88:89], v[150:151] op_sel_hi:[1,0]
	v_pk_fma_f32 v[72:73], v[72:73], v[148:149], v[66:67] op_sel_hi:[1,0,1]
	s_lshr_b32 s1, s100, 30
	s_add_i32 s1, s1, 3
	s_cmp_eq_u32 s74, s1
	v_pk_fma_f32 v[64:65], v[72:73], v[72:73], v[64:65]
	v_mul_f32_e32 v66, v73, v73
	v_pk_add_f32 v[64:65], v[66:67], v[64:65] op_sel_hi:[0,1]
	v_pk_fma_f32 v[64:65], v[74:75], v[74:75], v[64:65]
	v_mul_f32_e32 v66, v75, v75
	v_pk_add_f32 v[64:65], v[66:67], v[64:65] op_sel_hi:[0,1]
	v_pk_mul_f32 v[66:67], v[94:95], v[150:151] op_sel_hi:[1,0]
	s_waitcnt vmcnt(16) lgkmcnt(0)
	v_lshlrev_b32_e32 v116, 16, v160
	v_pk_fma_f32 v[68:69], v[78:79], v[148:149], v[66:67] op_sel_hi:[1,0,1]
	v_pk_mul_f32 v[66:67], v[92:93], v[150:151] op_sel_hi:[1,0]
	v_and_b32_e32 v117, 0xffff0000, v160
	v_pk_fma_f32 v[70:71], v[76:77], v[148:149], v[66:67] op_sel_hi:[1,0,1]
	s_nop 0
	v_pk_fma_f32 v[64:65], v[70:71], v[70:71], v[64:65]
	v_mul_f32_e32 v66, v71, v71
	v_pk_add_f32 v[64:65], v[66:67], v[64:65] op_sel_hi:[0,1]
	v_pk_fma_f32 v[64:65], v[68:69], v[68:69], v[64:65]
	v_mul_f32_e32 v66, v69, v69
	v_pk_add_f32 v[76:77], v[66:67], v[64:65] op_sel_hi:[0,1]
	v_pk_fma_f32 v[64:65], v[34:35], v[148:149], v[50:51] op_sel_hi:[1,0,1]
	v_pk_mul_f32 v[34:35], v[48:49], v[150:151] op_sel_hi:[1,0]
	s_nop 0
	v_pk_fma_f32 v[66:67], v[32:33], v[148:149], v[34:35] op_sel_hi:[1,0,1]
	s_nop 0
	v_pk_fma_f32 v[32:33], v[66:67], v[66:67], v[76:77]
	v_mul_f32_e32 v34, v67, v67
	v_pk_add_f32 v[32:33], v[34:35], v[32:33] op_sel_hi:[0,1]
	v_pk_fma_f32 v[32:33], v[64:65], v[64:65], v[32:33]
	v_mul_f32_e32 v34, v65, v65
	v_pk_add_f32 v[32:33], v[34:35], v[32:33] op_sel_hi:[0,1]
	v_pk_mul_f32 v[34:35], v[54:55], v[150:151] op_sel_hi:[1,0]
	s_nop 0
	v_pk_fma_f32 v[48:49], v[38:39], v[148:149], v[34:35] op_sel_hi:[1,0,1]
	v_pk_mul_f32 v[34:35], v[52:53], v[150:151] op_sel_hi:[1,0]
	s_nop 0
	v_pk_fma_f32 v[50:51], v[36:37], v[148:149], v[34:35] op_sel_hi:[1,0,1]
	s_nop 0
	v_pk_fma_f32 v[32:33], v[50:51], v[50:51], v[32:33]
	v_mul_f32_e32 v34, v51, v51
	v_pk_add_f32 v[32:33], v[34:35], v[32:33] op_sel_hi:[0,1]
	v_pk_fma_f32 v[32:33], v[48:49], v[48:49], v[32:33]
	v_mul_f32_e32 v34, v49, v49
	v_pk_add_f32 v[32:33], v[34:35], v[32:33] op_sel_hi:[0,1]
	v_pk_mul_f32 v[34:35], v[58:59], v[150:151] op_sel_hi:[1,0]
	s_nop 0
	v_pk_fma_f32 v[42:43], v[42:43], v[148:149], v[34:35] op_sel_hi:[1,0,1]
	v_pk_mul_f32 v[34:35], v[56:57], v[150:151] op_sel_hi:[1,0]
	s_nop 0
	v_pk_fma_f32 v[40:41], v[40:41], v[148:149], v[34:35] op_sel_hi:[1,0,1]
	s_nop 0
	v_pk_fma_f32 v[32:33], v[40:41], v[40:41], v[32:33]
	v_mul_f32_e32 v34, v41, v41
	v_pk_add_f32 v[32:33], v[34:35], v[32:33] op_sel_hi:[0,1]
	v_pk_fma_f32 v[32:33], v[42:43], v[42:43], v[32:33]
	v_mul_f32_e32 v34, v43, v43
	v_pk_add_f32 v[32:33], v[34:35], v[32:33] op_sel_hi:[0,1]
	v_pk_mul_f32 v[34:35], v[62:63], v[150:151] op_sel_hi:[1,0]
	s_nop 0
	v_pk_fma_f32 v[36:37], v[46:47], v[148:149], v[34:35] op_sel_hi:[1,0,1]
	v_pk_mul_f32 v[34:35], v[60:61], v[150:151] op_sel_hi:[1,0]
	s_nop 0
	v_pk_fma_f32 v[38:39], v[44:45], v[148:149], v[34:35] op_sel_hi:[1,0,1]
	s_nop 0
	v_pk_fma_f32 v[32:33], v[38:39], v[38:39], v[32:33]
	v_mul_f32_e32 v34, v39, v39
	v_pk_add_f32 v[32:33], v[34:35], v[32:33] op_sel_hi:[0,1]
	v_pk_fma_f32 v[32:33], v[36:37], v[36:37], v[32:33]
	v_mul_f32_e32 v34, v37, v37
	v_pk_add_f32 v[44:45], v[34:35], v[32:33] op_sel_hi:[0,1]
	v_pk_fma_f32 v[32:33], v[2:3], v[148:149], v[18:19] op_sel_hi:[1,0,1]
	v_pk_mul_f32 v[2:3], v[16:17], v[150:151] op_sel_hi:[1,0]
	s_nop 0
	v_pk_fma_f32 v[34:35], v[0:1], v[148:149], v[2:3] op_sel_hi:[1,0,1]
	s_nop 0
	v_pk_fma_f32 v[0:1], v[34:35], v[34:35], v[44:45]
	v_mul_f32_e32 v2, v35, v35
	v_pk_add_f32 v[0:1], v[2:3], v[0:1] op_sel_hi:[0,1]
	v_pk_fma_f32 v[0:1], v[32:33], v[32:33], v[0:1]
	v_mul_f32_e32 v2, v33, v33
	v_pk_add_f32 v[0:1], v[2:3], v[0:1] op_sel_hi:[0,1]
	v_pk_mul_f32 v[2:3], v[22:23], v[150:151] op_sel_hi:[1,0]
	v_lshlrev_b32_e32 v22, 16, v165
	v_pk_fma_f32 v[16:17], v[6:7], v[148:149], v[2:3] op_sel_hi:[1,0,1]
	v_pk_mul_f32 v[2:3], v[20:21], v[150:151] op_sel_hi:[1,0]
	v_and_b32_e32 v23, 0xffff0000, v165
	v_pk_fma_f32 v[18:19], v[4:5], v[148:149], v[2:3] op_sel_hi:[1,0,1]
	s_nop 0
	v_pk_fma_f32 v[0:1], v[18:19], v[18:19], v[0:1]
	v_mul_f32_e32 v2, v19, v19
	v_pk_add_f32 v[0:1], v[2:3], v[0:1] op_sel_hi:[0,1]
	v_pk_fma_f32 v[0:1], v[16:17], v[16:17], v[0:1]
	v_mul_f32_e32 v2, v17, v17
	v_pk_add_f32 v[0:1], v[2:3], v[0:1] op_sel_hi:[0,1]
	v_pk_mul_f32 v[2:3], v[26:27], v[150:151] op_sel_hi:[1,0]
	s_nop 0
	v_pk_fma_f32 v[10:11], v[10:11], v[148:149], v[2:3] op_sel_hi:[1,0,1]
	v_pk_mul_f32 v[2:3], v[24:25], v[150:151] op_sel_hi:[1,0]
	s_nop 0
	v_pk_fma_f32 v[8:9], v[8:9], v[148:149], v[2:3] op_sel_hi:[1,0,1]
	s_nop 0
	v_pk_fma_f32 v[0:1], v[8:9], v[8:9], v[0:1]
	v_mul_f32_e32 v2, v9, v9
	v_pk_add_f32 v[0:1], v[2:3], v[0:1] op_sel_hi:[0,1]
	v_pk_fma_f32 v[0:1], v[10:11], v[10:11], v[0:1]
	v_mul_f32_e32 v2, v11, v11
	v_pk_add_f32 v[4:5], v[2:3], v[0:1] op_sel_hi:[0,1]
	v_pk_mul_f32 v[2:3], v[28:29], v[150:151] op_sel_hi:[1,0]
	v_pk_mul_f32 v[0:1], v[30:31], v[150:151] op_sel_hi:[1,0]
	v_pk_fma_f32 v[2:3], v[12:13], v[148:149], v[2:3] op_sel_hi:[1,0,1]
	v_pk_fma_f32 v[0:1], v[14:15], v[148:149], v[0:1] op_sel_hi:[1,0,1]
	v_pk_fma_f32 v[4:5], v[2:3], v[2:3], v[4:5]
	v_mul_f32_e32 v6, v3, v3
	v_pk_add_f32 v[4:5], v[6:7], v[4:5] op_sel_hi:[0,1]
	v_pk_fma_f32 v[4:5], v[0:1], v[0:1], v[4:5]
	v_mul_f32_e32 v6, v1, v1
	v_pk_add_f32 v[4:5], v[6:7], v[4:5] op_sel_hi:[0,1]
	v_mov_b32_e32 v5, v4
	s_nop 1
	v_permlane32_swap_b32_e32 v4, v5
	v_add_f32_e32 v4, v4, v5
	v_fmamk_f32 v4, v4, 0x3c000000, v232
	v_mul_f32_e32 v5, 0x4b800000, v4
	v_cmp_gt_f32_e32 vcc, s0, v4
	v_lshlrev_b32_e32 v12, 16, v161
	v_and_b32_e32 v13, 0xffff0000, v161
	v_cndmask_b32_e32 v4, v4, v5, vcc
	v_rsq_f32_e32 v6, v4
	v_lshl_add_u64 v[4:5], v[140:141], 0, v[136:137]
	v_mul_f32_e32 v7, 0x45800000, v6
	v_cndmask_b32_e32 v6, v6, v7, vcc
	v_mul_f32_e32 v6, 0x3f077f5a, v6
	v_pk_mul_f32 v[14:15], v[112:113], v[6:7] op_sel_hi:[1,0]
	v_pk_mul_f32 v[20:21], v[114:115], v[6:7] op_sel_hi:[1,0]
	v_pk_mul_f32 v[14:15], v[128:129], v[14:15]
	v_pk_mul_f32 v[20:21], v[130:131], v[20:21]
	v_pk_mul_f32 v[14:15], v[14:15], v[116:117]
	v_pk_mul_f32 v[12:13], v[20:21], v[12:13]
	v_cvt_pk_bf16_f32 v14, v14, v15
	v_cvt_pk_bf16_f32 v15, v12, v13
	global_store_dwordx2 v[4:5], v[14:15], off
	ds_read_b128 v[12:15], v219 offset:32
	v_pk_mul_f32 v[20:21], v[100:101], v[6:7] op_sel_hi:[1,0]
	v_pk_mul_f32 v[24:25], v[104:105], v[6:7] op_sel_hi:[1,0]
	v_pk_mul_f32 v[26:27], v[106:107], v[6:7] op_sel_hi:[1,0]
	v_pk_mul_f32 v[28:29], v[110:111], v[6:7] op_sel_hi:[1,0]
	v_pk_mul_f32 v[30:31], v[98:99], v[6:7] op_sel_hi:[1,0]
	v_pk_mul_f32 v[44:45], v[96:97], v[6:7] op_sel_hi:[1,0]
	v_pk_mul_f32 v[32:33], v[32:33], v[6:7] op_sel_hi:[1,0]
	v_pk_mul_f32 v[18:19], v[18:19], v[6:7] op_sel_hi:[1,0]
	v_pk_mul_f32 v[16:17], v[16:17], v[6:7] op_sel_hi:[1,0]
	v_pk_mul_f32 v[8:9], v[8:9], v[6:7] op_sel_hi:[1,0]
	v_pk_mul_f32 v[10:11], v[10:11], v[6:7] op_sel_hi:[1,0]
	v_pk_mul_f32 v[2:3], v[2:3], v[6:7] op_sel_hi:[1,0]
	v_pk_mul_f32 v[0:1], v[0:1], v[6:7] op_sel_hi:[1,0]
	s_waitcnt lgkmcnt(0)
	v_pk_mul_f32 v[12:13], v[12:13], v[20:21]
	v_lshlrev_b32_e32 v20, 16, v162
	v_and_b32_e32 v21, 0xffff0000, v162
	v_pk_mul_f32 v[12:13], v[12:13], v[20:21]
	v_pk_mul_f32 v[20:21], v[102:103], v[6:7] op_sel_hi:[1,0]
	v_cvt_pk_bf16_f32 v12, v12, v13
	v_pk_mul_f32 v[14:15], v[14:15], v[20:21]
	v_lshlrev_b32_e32 v20, 16, v163
	v_and_b32_e32 v21, 0xffff0000, v163
	v_pk_mul_f32 v[14:15], v[14:15], v[20:21]
	v_lshlrev_b32_e32 v20, 16, v164
	v_cvt_pk_bf16_f32 v13, v14, v15
	global_store_dwordx2 v[4:5], v[12:13], off offset:16
	ds_read_b128 v[12:15], v219 offset:64
	v_and_b32_e32 v21, 0xffff0000, v164
	s_waitcnt lgkmcnt(0)
	v_pk_mul_f32 v[12:13], v[12:13], v[24:25]
	v_pk_mul_f32 v[14:15], v[14:15], v[26:27]
	v_pk_mul_f32 v[12:13], v[12:13], v[20:21]
	v_pk_mul_f32 v[14:15], v[14:15], v[22:23]
	v_cvt_pk_bf16_f32 v12, v12, v13
	v_cvt_pk_bf16_f32 v13, v14, v15
	global_store_dwordx2 v[4:5], v[12:13], off offset:32
	ds_read_b128 v[12:15], v219 offset:96
	s_nop 0
	v_pk_mul_f32 v[26:27], v[108:109], v[6:7] op_sel_hi:[1,0]
	v_lshlrev_b32_e32 v22, 16, v166
	v_and_b32_e32 v23, 0xffff0000, v166
	v_lshlrev_b32_e32 v24, 16, v167
	v_and_b32_e32 v25, 0xffff0000, v167
	s_waitcnt lgkmcnt(0)
	v_pk_mul_f32 v[12:13], v[12:13], v[26:27]
	v_pk_mul_f32 v[14:15], v[14:15], v[28:29]
	v_pk_mul_f32 v[12:13], v[12:13], v[22:23]
	v_pk_mul_f32 v[14:15], v[14:15], v[24:25]
	v_cvt_pk_bf16_f32 v12, v12, v13
	v_cvt_pk_bf16_f32 v13, v14, v15
	global_store_dwordx2 v[4:5], v[12:13], off offset:48
	ds_read_b128 v[12:15], v219 offset:128
	s_nop 0
	v_lshlrev_b32_e32 v28, 16, v168
	v_and_b32_e32 v29, 0xffff0000, v168
	v_lshlrev_b32_e32 v20, 16, v169
	v_and_b32_e32 v21, 0xffff0000, v169
	s_waitcnt lgkmcnt(0)
	v_pk_mul_f32 v[12:13], v[30:31], v[12:13]
	v_pk_mul_f32 v[14:15], v[44:45], v[14:15]
	v_pk_mul_f32 v[12:13], v[12:13], v[28:29]
	v_pk_mul_f32 v[14:15], v[14:15], v[20:21]
	v_cvt_pk_bf16_f32 v12, v12, v13
	v_cvt_pk_bf16_f32 v13, v14, v15
	global_store_dwordx2 v[4:5], v[12:13], off offset:64
	ds_read_b128 v[12:15], v219 offset:160
	v_pk_mul_f32 v[28:29], v[82:83], v[6:7] op_sel_hi:[1,0]
	v_pk_mul_f32 v[30:31], v[80:81], v[6:7] op_sel_hi:[1,0]
	v_lshlrev_b32_e32 v20, 16, v170
	v_and_b32_e32 v21, 0xffff0000, v170
	v_lshlrev_b32_e32 v22, 16, v171
	v_and_b32_e32 v23, 0xffff0000, v171
	v_pk_mul_f32 v[44:45], v[64:65], v[6:7] op_sel_hi:[1,0]
	s_waitcnt lgkmcnt(0)
	v_pk_mul_f32 v[12:13], v[28:29], v[12:13]
	v_pk_mul_f32 v[14:15], v[30:31], v[14:15]
	v_pk_mul_f32 v[12:13], v[12:13], v[20:21]
	v_pk_mul_f32 v[14:15], v[14:15], v[22:23]
	v_cvt_pk_bf16_f32 v12, v12, v13
	v_cvt_pk_bf16_f32 v13, v14, v15
	global_store_dwordx2 v[4:5], v[12:13], off offset:80
	ds_read_b128 v[12:15], v219 offset:192
	v_lshlrev_b32_e32 v20, 16, v172
	v_and_b32_e32 v21, 0xffff0000, v172
	v_lshlrev_b32_e32 v22, 16, v173
	v_and_b32_e32 v23, 0xffff0000, v173
	v_pk_mul_f32 v[24:25], v[72:73], v[6:7] op_sel_hi:[1,0]
	v_pk_mul_f32 v[28:29], v[74:75], v[6:7] op_sel_hi:[1,0]
	v_pk_mul_f32 v[30:31], v[66:67], v[6:7] op_sel_hi:[1,0]
	s_waitcnt lgkmcnt(0)
	v_pk_mul_f32 v[12:13], v[24:25], v[12:13]
	v_pk_mul_f32 v[14:15], v[28:29], v[14:15]
	v_pk_mul_f32 v[12:13], v[12:13], v[20:21]
	v_pk_mul_f32 v[14:15], v[14:15], v[22:23]
	v_cvt_pk_bf16_f32 v12, v12, v13
	v_cvt_pk_bf16_f32 v13, v14, v15
	global_store_dwordx2 v[4:5], v[12:13], off offset:96
	ds_read_b128 v[12:15], v219 offset:224
	s_nop 0
	v_lshlrev_b32_e32 v22, 16, v174
	v_and_b32_e32 v23, 0xffff0000, v174
	v_lshlrev_b32_e32 v24, 16, v175
	v_and_b32_e32 v25, 0xffff0000, v175
	v_pk_mul_f32 v[26:27], v[70:71], v[6:7] op_sel_hi:[1,0]
	v_pk_mul_f32 v[28:29], v[68:69], v[6:7] op_sel_hi:[1,0]
	s_waitcnt lgkmcnt(0)
	v_pk_mul_f32 v[12:13], v[26:27], v[12:13]
	v_pk_mul_f32 v[14:15], v[28:29], v[14:15]
	v_pk_mul_f32 v[12:13], v[12:13], v[22:23]
	v_pk_mul_f32 v[14:15], v[14:15], v[24:25]
	v_cvt_pk_bf16_f32 v12, v12, v13
	v_cvt_pk_bf16_f32 v13, v14, v15
	global_store_dwordx2 v[4:5], v[12:13], off offset:112
	ds_read_b128 v[12:15], v219 offset:256
	s_nop 0
	v_lshlrev_b32_e32 v28, 16, v202
	v_and_b32_e32 v29, 0xffff0000, v202
	v_lshlrev_b32_e32 v20, 16, v203
	v_and_b32_e32 v21, 0xffff0000, v203
	s_waitcnt lgkmcnt(0)
	v_pk_mul_f32 v[12:13], v[30:31], v[12:13]
	v_pk_mul_f32 v[14:15], v[44:45], v[14:15]
	v_pk_mul_f32 v[12:13], v[12:13], v[28:29]
	v_pk_mul_f32 v[14:15], v[14:15], v[20:21]
	v_cvt_pk_bf16_f32 v12, v12, v13
	v_cvt_pk_bf16_f32 v13, v14, v15
	global_store_dwordx2 v[4:5], v[12:13], off offset:128
	ds_read_b128 v[12:15], v219 offset:288
	v_pk_mul_f32 v[28:29], v[50:51], v[6:7] op_sel_hi:[1,0]
	v_pk_mul_f32 v[30:31], v[48:49], v[6:7] op_sel_hi:[1,0]
	v_lshlrev_b32_e32 v20, 16, v204
	v_and_b32_e32 v21, 0xffff0000, v204
	v_lshlrev_b32_e32 v22, 16, v205
	v_and_b32_e32 v23, 0xffff0000, v205
	s_waitcnt lgkmcnt(0)
	v_pk_mul_f32 v[12:13], v[28:29], v[12:13]
	v_pk_mul_f32 v[14:15], v[30:31], v[14:15]
	v_pk_mul_f32 v[12:13], v[12:13], v[20:21]
	v_pk_mul_f32 v[14:15], v[14:15], v[22:23]
	v_cvt_pk_bf16_f32 v12, v12, v13
	v_cvt_pk_bf16_f32 v13, v14, v15
	global_store_dwordx2 v[4:5], v[12:13], off offset:144
	ds_read_b128 v[12:15], v219 offset:320
	v_lshlrev_b32_e32 v20, 16, v244
	v_and_b32_e32 v21, 0xffff0000, v244
	v_lshlrev_b32_e32 v22, 16, v245
	v_and_b32_e32 v23, 0xffff0000, v245
	v_pk_mul_f32 v[24:25], v[40:41], v[6:7] op_sel_hi:[1,0]
	v_pk_mul_f32 v[28:29], v[42:43], v[6:7] op_sel_hi:[1,0]
	v_pk_mul_f32 v[30:31], v[34:35], v[6:7] op_sel_hi:[1,0]
	s_waitcnt lgkmcnt(0)
	v_pk_mul_f32 v[12:13], v[24:25], v[12:13]
	v_pk_mul_f32 v[14:15], v[28:29], v[14:15]
	v_pk_mul_f32 v[12:13], v[12:13], v[20:21]
	v_pk_mul_f32 v[14:15], v[14:15], v[22:23]
	v_cvt_pk_bf16_f32 v12, v12, v13
	v_cvt_pk_bf16_f32 v13, v14, v15
	global_store_dwordx2 v[4:5], v[12:13], off offset:160
	ds_read_b128 v[12:15], v219 offset:352
	s_nop 0
	v_lshlrev_b32_e32 v22, 16, v246
	v_and_b32_e32 v23, 0xffff0000, v246
	v_lshlrev_b32_e32 v24, 16, v247
	v_and_b32_e32 v25, 0xffff0000, v247
	v_pk_mul_f32 v[26:27], v[38:39], v[6:7] op_sel_hi:[1,0]
	v_pk_mul_f32 v[28:29], v[36:37], v[6:7] op_sel_hi:[1,0]
	s_waitcnt lgkmcnt(0)
	v_pk_mul_f32 v[12:13], v[26:27], v[12:13]
	v_pk_mul_f32 v[14:15], v[28:29], v[14:15]
	v_pk_mul_f32 v[12:13], v[12:13], v[22:23]
	v_pk_mul_f32 v[14:15], v[14:15], v[24:25]
	v_cvt_pk_bf16_f32 v12, v12, v13
	v_cvt_pk_bf16_f32 v13, v14, v15
	global_store_dwordx2 v[4:5], v[12:13], off offset:176
	ds_read_b128 v[12:15], v219 offset:384
	s_nop 0
	v_lshlrev_b32_e32 v28, 16, v248
	v_and_b32_e32 v29, 0xffff0000, v248
	v_lshlrev_b32_e32 v20, 16, v249
	v_and_b32_e32 v21, 0xffff0000, v249
	s_waitcnt lgkmcnt(0)
	v_pk_mul_f32 v[12:13], v[30:31], v[12:13]
	v_pk_mul_f32 v[14:15], v[32:33], v[14:15]
	v_pk_mul_f32 v[12:13], v[12:13], v[28:29]
	v_pk_mul_f32 v[14:15], v[14:15], v[20:21]
	v_cvt_pk_bf16_f32 v12, v12, v13
	v_cvt_pk_bf16_f32 v13, v14, v15
	global_store_dwordx2 v[4:5], v[12:13], off offset:192
	ds_read_b128 v[12:15], v219 offset:416
	v_lshlrev_b32_e32 v20, 16, v250
	v_and_b32_e32 v21, 0xffff0000, v250
	v_lshlrev_b32_e32 v22, 16, v251
	v_and_b32_e32 v23, 0xffff0000, v251
	s_waitcnt lgkmcnt(0)
	v_pk_mul_f32 v[12:13], v[18:19], v[12:13]
	v_pk_mul_f32 v[14:15], v[16:17], v[14:15]
	v_pk_mul_f32 v[12:13], v[12:13], v[20:21]
	v_pk_mul_f32 v[14:15], v[14:15], v[22:23]
	v_cvt_pk_bf16_f32 v12, v12, v13
	v_cvt_pk_bf16_f32 v13, v14, v15
	global_store_dwordx2 v[4:5], v[12:13], off offset:208
	ds_read_b128 v[12:15], v219 offset:448
	v_lshlrev_b32_e32 v16, 16, v252
	v_and_b32_e32 v17, 0xffff0000, v252
	v_lshlrev_b32_e32 v18, 16, v253
	v_and_b32_e32 v19, 0xffff0000, v253
	s_waitcnt lgkmcnt(0)
	v_pk_mul_f32 v[8:9], v[8:9], v[12:13]
	v_pk_mul_f32 v[10:11], v[10:11], v[14:15]
	v_pk_mul_f32 v[8:9], v[8:9], v[16:17]
	v_pk_mul_f32 v[10:11], v[10:11], v[18:19]
	v_cvt_pk_bf16_f32 v8, v8, v9
	v_cvt_pk_bf16_f32 v9, v10, v11
	global_store_dwordx2 v[4:5], v[8:9], off offset:224
	ds_read_b128 v[8:11], v219 offset:480
	v_lshlrev_b32_e32 v12, 16, v254
	v_and_b32_e32 v13, 0xffff0000, v254
	v_lshlrev_b32_e32 v14, 16, v255
	v_and_b32_e32 v15, 0xffff0000, v255
	s_waitcnt lgkmcnt(0)
	v_pk_mul_f32 v[2:3], v[2:3], v[8:9]
	v_pk_mul_f32 v[0:1], v[0:1], v[10:11]
	v_pk_mul_f32 v[2:3], v[2:3], v[12:13]
	v_pk_mul_f32 v[0:1], v[0:1], v[14:15]
	v_cvt_pk_bf16_f32 v2, v2, v3
	v_cvt_pk_bf16_f32 v3, v0, v1
	global_store_dwordx2 v[4:5], v[2:3], off offset:240
	s_cbranch_scc1 .LBB0_735
	s_branch .LBB0_736

.Lat1_go:
	v_sub_f32_e32 v180, v200, v199
	v_sub_f32_e32 v198, v200, v201
	s_nop 0
	v_max3_f32 v217, v144, v145, v146
	v_max3_f32 v219, v160, v161, v162
	v_max3_f32 v221, v147, v148, v149
	v_max3_f32 v225, v163, v164, v165
	v_max3_f32 v223, v150, v151, v152
	v_max3_f32 v229, v166, v167, v168
	v_add_f32_e32 v144, v144, v180
	v_add_f32_e32 v160, v160, v198
	v_max3_f32 v217, v217, v221, v223
	v_exp_f32_e32 v144, v144
	v_exp_f32_e32 v160, v160
	v_max3_f32 v219, v219, v225, v229
	v_add_f32_e32 v145, v145, v180
	v_add_f32_e32 v161, v161, v198
	v_max3_f32 v221, v153, v154, v155
	v_exp_f32_e32 v145, v145
	v_exp_f32_e32 v161, v161
	v_max3_f32 v225, v169, v170, v171
	v_add_f32_e32 v146, v146, v180
	v_add_f32_e32 v162, v162, v198
	v_max3_f32 v223, v156, v157, v158
	v_exp_f32_e32 v146, v146
	v_exp_f32_e32 v162, v162
	v_max3_f32 v229, v172, v173, v174
	v_add_f32_e32 v147, v147, v180
	v_add_f32_e32 v163, v163, v198
	v_max3_f32 v221, v221, v223, v159
	v_exp_f32_e32 v147, v147
	v_exp_f32_e32 v163, v163
	v_max3_f32 v225, v225, v229, v175
	v_add_f32_e32 v148, v148, v180
	v_add_f32_e32 v164, v164, v198
	v_max_f32_e32 v217, v217, v221
	v_exp_f32_e32 v148, v148
	v_exp_f32_e32 v164, v164
	v_max_f32_e32 v219, v219, v225
	v_add_f32_e32 v149, v149, v180
	v_add_f32_e32 v165, v165, v198
	v_add_f32_e32 v221, v200, v217
	v_exp_f32_e32 v149, v149
	v_exp_f32_e32 v165, v165
	v_add_f32_e32 v225, v200, v219
	v_add_f32_e32 v150, v150, v180
	v_add_f32_e32 v166, v166, v198
	v_cmp_gt_f32_e32 vcc, v221, v227
	v_exp_f32_e32 v150, v150
	v_exp_f32_e32 v166, v166
	v_cmp_gt_f32_e64 s[0:1], v225, v215
	v_sub_f32_e32 v223, v221, v227
	v_sub_f32_e32 v229, v225, v215
	v_max_f32_e32 v223, v223, v229
	v_add_f32_e32 v223, 0x43080000, v223
	v_cmp_nlt_f32_e64 s[98:99], v223, 0
	v_add_f32_e32 v151, v151, v180
	v_add_f32_e32 v167, v167, v198
	v_exp_f32_e32 v151, v151
	v_exp_f32_e32 v167, v167
	v_add_f32_e32 v215, v144, v145
	v_add_f32_e32 v217, v160, v161
	v_add_f32_e32 v215, v215, v146
	v_add_f32_e32 v217, v217, v162
	v_add_f32_e32 v215, v215, v147
	v_add_f32_e32 v217, v217, v163
	v_add_f32_e32 v215, v215, v148
	v_add_f32_e32 v217, v217, v164
	v_add_f32_e32 v215, v215, v149
	v_add_f32_e32 v217, v217, v165
	v_add_f32_e32 v215, v215, v150
	v_add_f32_e32 v217, v217, v166
	v_add_f32_e32 v215, v215, v151
	v_add_f32_e32 v217, v217, v167
	v_cvt_pk_bf16_f32 v144, v144, v145
	v_cvt_pk_bf16_f32 v160, v160, v161
	v_cvt_pk_bf16_f32 v145, v146, v147
	v_cvt_pk_bf16_f32 v161, v162, v163
	v_cvt_pk_bf16_f32 v146, v148, v149
	v_cvt_pk_bf16_f32 v162, v164, v165
	v_cvt_pk_bf16_f32 v147, v150, v151
	v_cvt_pk_bf16_f32 v163, v166, v167
	ds_read_b64_tr_b16 v[148:149], v216 offset:12288
	ds_read_b64_tr_b16 v[150:151], v218 offset:12288
	ds_read_b64_tr_b16 v[164:165], v220 offset:12288
	ds_read_b64_tr_b16 v[166:167], v222 offset:12288
	s_or_b64 vcc, vcc, s[0:1]
	s_cbranch_vccnz .Lat1_redo
	s_cmp_eq_u64 s[98:99], 0
	s_cselect_b32 s51, 1, 0
	s_cbranch_scc1 .Lat1_skip
	s_waitcnt lgkmcnt(4)
	v_mfma_f32_32x32x16_bf16 v[112:127], v[202:205], v[144:147], v[112:127]
	v_add_f32_e32 v152, v152, v180
	v_add_f32_e32 v168, v168, v198
	v_exp_f32_e32 v152, v152
	v_exp_f32_e32 v168, v168
	v_mfma_f32_32x32x16_bf16 v[96:111], v[202:205], v[160:163], v[96:111]
	v_add_f32_e32 v153, v153, v180
	v_add_f32_e32 v169, v169, v198
	v_exp_f32_e32 v153, v153
	v_exp_f32_e32 v169, v169
	ds_read_b64_tr_b16 v[202:203], v224 offset:12288
	ds_read_b64_tr_b16 v[204:205], v226 offset:12288
	v_mfma_f32_32x32x16_bf16 v[64:79], v[244:247], v[144:147], v[64:79]
	v_add_f32_e32 v154, v154, v180
	v_add_f32_e32 v170, v170, v198
	v_exp_f32_e32 v154, v154
	v_exp_f32_e32 v170, v170
	v_mfma_f32_32x32x16_bf16 v[80:95], v[244:247], v[160:163], v[80:95]
	v_add_f32_e32 v155, v155, v180
	v_add_f32_e32 v171, v171, v198
	v_exp_f32_e32 v155, v155
	v_exp_f32_e32 v171, v171
	ds_read_b64_tr_b16 v[244:245], v228 offset:12288
	ds_read_b64_tr_b16 v[246:247], v230 offset:12288
	v_mfma_f32_32x32x16_bf16 v[32:47], v[248:251], v[144:147], v[32:47]
	v_add_f32_e32 v156, v156, v180
	v_add_f32_e32 v172, v172, v198
	v_exp_f32_e32 v156, v156
	v_exp_f32_e32 v172, v172
	v_mfma_f32_32x32x16_bf16 v[48:63], v[248:251], v[160:163], v[48:63]
	v_add_f32_e32 v157, v157, v180
	v_add_f32_e32 v173, v173, v198
	v_exp_f32_e32 v157, v157
	v_exp_f32_e32 v173, v173
	v_mfma_f32_32x32x16_bf16 v[0:15], v[252:255], v[144:147], v[0:15]
	v_add_f32_e32 v158, v158, v180
	v_add_f32_e32 v174, v174, v198
	v_exp_f32_e32 v158, v158
	v_exp_f32_e32 v174, v174
	v_mfma_f32_32x32x16_bf16 v[16:31], v[252:255], v[160:163], v[16:31]
	v_add_f32_e32 v159, v159, v180
	v_add_f32_e32 v175, v175, v198
	v_exp_f32_e32 v159, v159
	v_exp_f32_e32 v175, v175
	v_cvt_pk_bf16_f32 v248, v152, v153
	v_cvt_pk_bf16_f32 v252, v168, v169
	v_cvt_pk_bf16_f32 v249, v154, v155
	v_cvt_pk_bf16_f32 v253, v170, v171
	v_cvt_pk_bf16_f32 v250, v156, v157
	v_cvt_pk_bf16_f32 v254, v172, v173
	v_cvt_pk_bf16_f32 v251, v158, v159
	v_cvt_pk_bf16_f32 v255, v174, v175
	s_nop 0
	s_waitcnt lgkmcnt(6)
	v_mfma_f32_32x32x16_bf16 v[112:127], v[148:151], v[248:251], v[112:127]
	v_add_f32_e32 v215, v215, v152
	v_add_f32_e32 v217, v217, v168
	v_mfma_f32_32x32x16_bf16 v[96:111], v[148:151], v[252:255], v[96:111]
	v_add_f32_e32 v215, v215, v153
	v_add_f32_e32 v217, v217, v169
	v_add_f32_e32 v215, v215, v154
	s_waitcnt lgkmcnt(4)
	v_mfma_f32_32x32x16_bf16 v[64:79], v[164:167], v[248:251], v[64:79]
	v_add_f32_e32 v217, v217, v170
	v_add_f32_e32 v215, v215, v155
	v_mfma_f32_32x32x16_bf16 v[80:95], v[164:167], v[252:255], v[80:95]
	v_add_f32_e32 v217, v217, v171
	v_add_f32_e32 v215, v215, v156
	v_add_f32_e32 v217, v217, v172
	s_waitcnt lgkmcnt(2)
	v_mfma_f32_32x32x16_bf16 v[32:47], v[202:205], v[248:251], v[32:47]
	v_add_f32_e32 v215, v215, v157
	v_add_f32_e32 v217, v217, v173
	v_mfma_f32_32x32x16_bf16 v[48:63], v[202:205], v[252:255], v[48:63]
	v_add_f32_e32 v215, v215, v158
	v_add_f32_e32 v217, v217, v174
	v_add_f32_e32 v215, v215, v159
	s_waitcnt lgkmcnt(0)
	v_mfma_f32_32x32x16_bf16 v[0:15], v[244:247], v[248:251], v[0:15]
	v_add_f32_e32 v217, v217, v175
	v_add_f32_e32 v197, v197, v215
	v_mfma_f32_32x32x16_bf16 v[16:31], v[244:247], v[252:255], v[16:31]
	v_add_f32_e32 v196, v196, v217

.Lat2_go:
	v_sub_f32_e32 v180, v200, v199
	v_sub_f32_e32 v198, v200, v201
	s_nop 0
	v_max3_f32 v217, v144, v145, v146
	v_max3_f32 v219, v160, v161, v162
	v_max3_f32 v221, v147, v148, v149
	v_max3_f32 v225, v163, v164, v165
	v_max3_f32 v223, v150, v151, v152
	v_max3_f32 v229, v166, v167, v168
	v_add_f32_e32 v144, v144, v180
	v_add_f32_e32 v160, v160, v198
	v_max3_f32 v217, v217, v221, v223
	v_exp_f32_e32 v144, v144
	v_exp_f32_e32 v160, v160
	v_max3_f32 v219, v219, v225, v229
	v_add_f32_e32 v145, v145, v180
	v_add_f32_e32 v161, v161, v198
	v_max3_f32 v221, v153, v154, v155
	v_exp_f32_e32 v145, v145
	v_exp_f32_e32 v161, v161
	v_max3_f32 v225, v169, v170, v171
	v_add_f32_e32 v146, v146, v180
	v_add_f32_e32 v162, v162, v198
	v_max3_f32 v223, v156, v157, v158
	v_exp_f32_e32 v146, v146
	v_exp_f32_e32 v162, v162
	v_max3_f32 v229, v172, v173, v174
	v_add_f32_e32 v147, v147, v180
	v_add_f32_e32 v163, v163, v198
	v_max3_f32 v221, v221, v223, v159
	v_exp_f32_e32 v147, v147
	v_exp_f32_e32 v163, v163
	v_max3_f32 v225, v225, v229, v175
	v_add_f32_e32 v148, v148, v180
	v_add_f32_e32 v164, v164, v198
	v_max_f32_e32 v217, v217, v221
	v_exp_f32_e32 v148, v148
	v_exp_f32_e32 v164, v164
	v_max_f32_e32 v219, v219, v225
	v_add_f32_e32 v149, v149, v180
	v_add_f32_e32 v165, v165, v198
	v_add_f32_e32 v221, v200, v217
	v_exp_f32_e32 v149, v149
	v_exp_f32_e32 v165, v165
	v_add_f32_e32 v225, v200, v219
	v_add_f32_e32 v150, v150, v180
	v_add_f32_e32 v166, v166, v198
	v_cmp_gt_f32_e32 vcc, v221, v227
	v_exp_f32_e32 v150, v150
	v_exp_f32_e32 v166, v166
	v_cmp_gt_f32_e64 s[0:1], v225, v215
	v_sub_f32_e32 v223, v221, v227
	v_sub_f32_e32 v229, v225, v215
	v_max_f32_e32 v223, v223, v229
	v_add_f32_e32 v223, 0x43080000, v223
	v_cmp_nlt_f32_e64 s[98:99], v223, 0
	v_add_f32_e32 v151, v151, v180
	v_add_f32_e32 v167, v167, v198
	v_exp_f32_e32 v151, v151
	v_exp_f32_e32 v167, v167
	v_add_f32_e32 v215, v144, v145
	v_add_f32_e32 v217, v160, v161
	v_add_f32_e32 v215, v215, v146
	v_add_f32_e32 v217, v217, v162
	v_add_f32_e32 v215, v215, v147
	v_add_f32_e32 v217, v217, v163
	v_add_f32_e32 v215, v215, v148
	v_add_f32_e32 v217, v217, v164
	v_add_f32_e32 v215, v215, v149
	v_add_f32_e32 v217, v217, v165
	v_add_f32_e32 v215, v215, v150
	v_add_f32_e32 v217, v217, v166
	v_add_f32_e32 v215, v215, v151
	v_add_f32_e32 v217, v217, v167
	v_cvt_pk_bf16_f32 v144, v144, v145
	v_cvt_pk_bf16_f32 v160, v160, v161
	v_cvt_pk_bf16_f32 v145, v146, v147
	v_cvt_pk_bf16_f32 v161, v162, v163
	v_cvt_pk_bf16_f32 v146, v148, v149
	v_cvt_pk_bf16_f32 v162, v164, v165
	v_cvt_pk_bf16_f32 v147, v150, v151
	v_cvt_pk_bf16_f32 v163, v166, v167
	ds_read_b64_tr_b16 v[148:149], v216 offset:4096
	ds_read_b64_tr_b16 v[150:151], v218 offset:4096
	ds_read_b64_tr_b16 v[164:165], v220 offset:4096
	ds_read_b64_tr_b16 v[166:167], v222 offset:4096
	s_or_b64 vcc, vcc, s[0:1]
	s_cbranch_vccnz .Lat2_redo
	s_cmp_eq_u64 s[98:99], 0
	s_cselect_b32 s51, 1, 0
	s_cbranch_scc1 .Lat2_skip
	s_waitcnt lgkmcnt(4)
	v_mfma_f32_32x32x16_bf16 v[112:127], v[202:205], v[144:147], v[112:127]
	v_add_f32_e32 v152, v152, v180
	v_add_f32_e32 v168, v168, v198
	v_exp_f32_e32 v152, v152
	v_exp_f32_e32 v168, v168
	v_mfma_f32_32x32x16_bf16 v[96:111], v[202:205], v[160:163], v[96:111]
	v_add_f32_e32 v153, v153, v180
	v_add_f32_e32 v169, v169, v198
	v_exp_f32_e32 v153, v153
	v_exp_f32_e32 v169, v169
	ds_read_b64_tr_b16 v[202:203], v224 offset:4096
	ds_read_b64_tr_b16 v[204:205], v226 offset:4096
	v_mfma_f32_32x32x16_bf16 v[64:79], v[244:247], v[144:147], v[64:79]
	v_add_f32_e32 v154, v154, v180
	v_add_f32_e32 v170, v170, v198
	v_exp_f32_e32 v154, v154
	v_exp_f32_e32 v170, v170
	v_mfma_f32_32x32x16_bf16 v[80:95], v[244:247], v[160:163], v[80:95]
	v_add_f32_e32 v155, v155, v180
	v_add_f32_e32 v171, v171, v198
	v_exp_f32_e32 v155, v155
	v_exp_f32_e32 v171, v171
	ds_read_b64_tr_b16 v[244:245], v228 offset:4096
	ds_read_b64_tr_b16 v[246:247], v230 offset:4096
	v_mfma_f32_32x32x16_bf16 v[32:47], v[248:251], v[144:147], v[32:47]
	v_add_f32_e32 v156, v156, v180
	v_add_f32_e32 v172, v172, v198
	v_exp_f32_e32 v156, v156
	v_exp_f32_e32 v172, v172
	v_mfma_f32_32x32x16_bf16 v[48:63], v[248:251], v[160:163], v[48:63]
	v_add_f32_e32 v157, v157, v180
	v_add_f32_e32 v173, v173, v198
	v_exp_f32_e32 v157, v157
	v_exp_f32_e32 v173, v173
	v_mfma_f32_32x32x16_bf16 v[0:15], v[252:255], v[144:147], v[0:15]
	v_add_f32_e32 v158, v158, v180
	v_add_f32_e32 v174, v174, v198
	v_exp_f32_e32 v158, v158
	v_exp_f32_e32 v174, v174
	v_mfma_f32_32x32x16_bf16 v[16:31], v[252:255], v[160:163], v[16:31]
	v_add_f32_e32 v159, v159, v180
	v_add_f32_e32 v175, v175, v198
	v_exp_f32_e32 v159, v159
	v_exp_f32_e32 v175, v175
	v_cvt_pk_bf16_f32 v248, v152, v153
	v_cvt_pk_bf16_f32 v252, v168, v169
	v_cvt_pk_bf16_f32 v249, v154, v155
	v_cvt_pk_bf16_f32 v253, v170, v171
	v_cvt_pk_bf16_f32 v250, v156, v157
	v_cvt_pk_bf16_f32 v254, v172, v173
	v_cvt_pk_bf16_f32 v251, v158, v159
	v_cvt_pk_bf16_f32 v255, v174, v175
	s_nop 0
	s_waitcnt lgkmcnt(6)
	v_mfma_f32_32x32x16_bf16 v[112:127], v[148:151], v[248:251], v[112:127]
	v_add_f32_e32 v215, v215, v152
	v_add_f32_e32 v217, v217, v168
	v_mfma_f32_32x32x16_bf16 v[96:111], v[148:151], v[252:255], v[96:111]
	v_add_f32_e32 v215, v215, v153
	v_add_f32_e32 v217, v217, v169
	v_add_f32_e32 v215, v215, v154
	s_waitcnt lgkmcnt(4)
	v_mfma_f32_32x32x16_bf16 v[64:79], v[164:167], v[248:251], v[64:79]
	v_add_f32_e32 v217, v217, v170
	v_add_f32_e32 v215, v215, v155
	v_mfma_f32_32x32x16_bf16 v[80:95], v[164:167], v[252:255], v[80:95]
	v_add_f32_e32 v217, v217, v171
	v_add_f32_e32 v215, v215, v156
	v_add_f32_e32 v217, v217, v172
	s_waitcnt lgkmcnt(2)
	v_mfma_f32_32x32x16_bf16 v[32:47], v[202:205], v[248:251], v[32:47]
	v_add_f32_e32 v215, v215, v157
	v_add_f32_e32 v217, v217, v173
	v_mfma_f32_32x32x16_bf16 v[48:63], v[202:205], v[252:255], v[48:63]
	v_add_f32_e32 v215, v215, v158
	v_add_f32_e32 v217, v217, v174
	v_add_f32_e32 v215, v215, v159
	s_waitcnt lgkmcnt(0)
	v_mfma_f32_32x32x16_bf16 v[0:15], v[244:247], v[248:251], v[0:15]
	v_add_f32_e32 v217, v217, v175
	v_add_f32_e32 v197, v197, v215
	v_mfma_f32_32x32x16_bf16 v[16:31], v[244:247], v[252:255], v[16:31]
	v_add_f32_e32 v196, v196, v217

.Lat3_go:
	v_sub_f32_e32 v180, v200, v199
	v_sub_f32_e32 v198, v200, v201
	s_nop 0
	v_max3_f32 v217, v144, v145, v146
	v_max3_f32 v219, v160, v161, v162
	v_max3_f32 v221, v147, v148, v149
	v_max3_f32 v225, v163, v164, v165
	v_max3_f32 v223, v150, v151, v152
	v_max3_f32 v229, v166, v167, v168
	v_add_f32_e32 v144, v144, v180
	v_add_f32_e32 v160, v160, v198
	v_max3_f32 v217, v217, v221, v223
	v_exp_f32_e32 v144, v144
	v_exp_f32_e32 v160, v160
	v_max3_f32 v219, v219, v225, v229
	v_add_f32_e32 v145, v145, v180
	v_add_f32_e32 v161, v161, v198
	v_max3_f32 v221, v153, v154, v155
	v_exp_f32_e32 v145, v145
	v_exp_f32_e32 v161, v161
	v_max3_f32 v225, v169, v170, v171
	v_add_f32_e32 v146, v146, v180
	v_add_f32_e32 v162, v162, v198
	v_max3_f32 v223, v156, v157, v158
	v_exp_f32_e32 v146, v146
	v_exp_f32_e32 v162, v162
	v_max3_f32 v229, v172, v173, v174
	v_add_f32_e32 v147, v147, v180
	v_add_f32_e32 v163, v163, v198
	v_max3_f32 v221, v221, v223, v159
	v_exp_f32_e32 v147, v147
	v_exp_f32_e32 v163, v163
	v_max3_f32 v225, v225, v229, v175
	v_add_f32_e32 v148, v148, v180
	v_add_f32_e32 v164, v164, v198
	v_max_f32_e32 v217, v217, v221
	v_exp_f32_e32 v148, v148
	v_exp_f32_e32 v164, v164
	v_max_f32_e32 v219, v219, v225
	v_add_f32_e32 v149, v149, v180
	v_add_f32_e32 v165, v165, v198
	v_add_f32_e32 v221, v200, v217
	v_exp_f32_e32 v149, v149
	v_exp_f32_e32 v165, v165
	v_add_f32_e32 v225, v200, v219
	v_add_f32_e32 v150, v150, v180
	v_add_f32_e32 v166, v166, v198
	v_cmp_gt_f32_e32 vcc, v221, v227
	v_exp_f32_e32 v150, v150
	v_exp_f32_e32 v166, v166
	v_cmp_gt_f32_e64 s[0:1], v225, v215
	v_sub_f32_e32 v223, v221, v227
	v_sub_f32_e32 v229, v225, v215
	v_max_f32_e32 v223, v223, v229
	v_add_f32_e32 v223, 0x43080000, v223
	v_cmp_nlt_f32_e64 s[98:99], v223, 0
	v_add_f32_e32 v151, v151, v180
	v_add_f32_e32 v167, v167, v198
	v_exp_f32_e32 v151, v151
	v_exp_f32_e32 v167, v167
	v_add_f32_e32 v215, v144, v145
	v_add_f32_e32 v217, v160, v161
	v_add_f32_e32 v215, v215, v146
	v_add_f32_e32 v217, v217, v162
	v_add_f32_e32 v215, v215, v147
	v_add_f32_e32 v217, v217, v163
	v_add_f32_e32 v215, v215, v148
	v_add_f32_e32 v217, v217, v164
	v_add_f32_e32 v215, v215, v149
	v_add_f32_e32 v217, v217, v165
	v_add_f32_e32 v215, v215, v150
	v_add_f32_e32 v217, v217, v166
	v_add_f32_e32 v215, v215, v151
	v_add_f32_e32 v217, v217, v167
	v_cvt_pk_bf16_f32 v144, v144, v145
	v_cvt_pk_bf16_f32 v160, v160, v161
	v_cvt_pk_bf16_f32 v145, v146, v147
	v_cvt_pk_bf16_f32 v161, v162, v163
	v_cvt_pk_bf16_f32 v146, v148, v149
	v_cvt_pk_bf16_f32 v162, v164, v165
	v_cvt_pk_bf16_f32 v147, v150, v151
	v_cvt_pk_bf16_f32 v163, v166, v167
	ds_read_b64_tr_b16 v[148:149], v216 offset:28672
	ds_read_b64_tr_b16 v[150:151], v218 offset:28672
	ds_read_b64_tr_b16 v[164:165], v220 offset:28672
	ds_read_b64_tr_b16 v[166:167], v222 offset:28672
	s_or_b64 vcc, vcc, s[0:1]
	s_cbranch_vccnz .Lat3_redo
	s_cmp_eq_u64 s[98:99], 0
	s_cselect_b32 s51, 1, 0
	s_cbranch_scc1 .Lat3_skip
	s_waitcnt lgkmcnt(4)
	v_mfma_f32_32x32x16_bf16 v[112:127], v[202:205], v[144:147], v[112:127]
	v_add_f32_e32 v152, v152, v180
	v_add_f32_e32 v168, v168, v198
	v_exp_f32_e32 v152, v152
	v_exp_f32_e32 v168, v168
	v_mfma_f32_32x32x16_bf16 v[96:111], v[202:205], v[160:163], v[96:111]
	v_add_f32_e32 v153, v153, v180
	v_add_f32_e32 v169, v169, v198
	v_exp_f32_e32 v153, v153
	v_exp_f32_e32 v169, v169
	ds_read_b64_tr_b16 v[202:203], v224 offset:28672
	ds_read_b64_tr_b16 v[204:205], v226 offset:28672
	v_mfma_f32_32x32x16_bf16 v[64:79], v[244:247], v[144:147], v[64:79]
	v_add_f32_e32 v154, v154, v180
	v_add_f32_e32 v170, v170, v198
	v_exp_f32_e32 v154, v154
	v_exp_f32_e32 v170, v170
	v_mfma_f32_32x32x16_bf16 v[80:95], v[244:247], v[160:163], v[80:95]
	v_add_f32_e32 v155, v155, v180
	v_add_f32_e32 v171, v171, v198
	v_exp_f32_e32 v155, v155
	v_exp_f32_e32 v171, v171
	ds_read_b64_tr_b16 v[244:245], v228 offset:28672
	ds_read_b64_tr_b16 v[246:247], v230 offset:28672
	v_mfma_f32_32x32x16_bf16 v[32:47], v[248:251], v[144:147], v[32:47]
	v_add_f32_e32 v156, v156, v180
	v_add_f32_e32 v172, v172, v198
	v_exp_f32_e32 v156, v156
	v_exp_f32_e32 v172, v172
	v_mfma_f32_32x32x16_bf16 v[48:63], v[248:251], v[160:163], v[48:63]
	v_add_f32_e32 v157, v157, v180
	v_add_f32_e32 v173, v173, v198
	v_exp_f32_e32 v157, v157
	v_exp_f32_e32 v173, v173
	v_mfma_f32_32x32x16_bf16 v[0:15], v[252:255], v[144:147], v[0:15]
	v_add_f32_e32 v158, v158, v180
	v_add_f32_e32 v174, v174, v198
	v_exp_f32_e32 v158, v158
	v_exp_f32_e32 v174, v174
	v_mfma_f32_32x32x16_bf16 v[16:31], v[252:255], v[160:163], v[16:31]
	v_add_f32_e32 v159, v159, v180
	v_add_f32_e32 v175, v175, v198
	v_exp_f32_e32 v159, v159
	v_exp_f32_e32 v175, v175
	v_cvt_pk_bf16_f32 v248, v152, v153
	v_cvt_pk_bf16_f32 v252, v168, v169
	v_cvt_pk_bf16_f32 v249, v154, v155
	v_cvt_pk_bf16_f32 v253, v170, v171
	v_cvt_pk_bf16_f32 v250, v156, v157
	v_cvt_pk_bf16_f32 v254, v172, v173
	v_cvt_pk_bf16_f32 v251, v158, v159
	v_cvt_pk_bf16_f32 v255, v174, v175
	s_nop 0
	s_waitcnt lgkmcnt(6)
	v_mfma_f32_32x32x16_bf16 v[112:127], v[148:151], v[248:251], v[112:127]
	v_add_f32_e32 v215, v215, v152
	v_add_f32_e32 v217, v217, v168
	v_mfma_f32_32x32x16_bf16 v[96:111], v[148:151], v[252:255], v[96:111]
	v_add_f32_e32 v215, v215, v153
	v_add_f32_e32 v217, v217, v169
	v_add_f32_e32 v215, v215, v154
	s_waitcnt lgkmcnt(4)
	v_mfma_f32_32x32x16_bf16 v[64:79], v[164:167], v[248:251], v[64:79]
	v_add_f32_e32 v217, v217, v170
	v_add_f32_e32 v215, v215, v155
	v_mfma_f32_32x32x16_bf16 v[80:95], v[164:167], v[252:255], v[80:95]
	v_add_f32_e32 v217, v217, v171
	v_add_f32_e32 v215, v215, v156
	v_add_f32_e32 v217, v217, v172
	s_waitcnt lgkmcnt(2)
	v_mfma_f32_32x32x16_bf16 v[32:47], v[202:205], v[248:251], v[32:47]
	v_add_f32_e32 v215, v215, v157
	v_add_f32_e32 v217, v217, v173
	v_mfma_f32_32x32x16_bf16 v[48:63], v[202:205], v[252:255], v[48:63]
	v_add_f32_e32 v215, v215, v158
	v_add_f32_e32 v217, v217, v174
	v_add_f32_e32 v215, v215, v159
	s_waitcnt lgkmcnt(0)
	v_mfma_f32_32x32x16_bf16 v[0:15], v[244:247], v[248:251], v[0:15]
	v_add_f32_e32 v217, v217, v175
	v_add_f32_e32 v197, v197, v215
	v_mfma_f32_32x32x16_bf16 v[16:31], v[244:247], v[252:255], v[16:31]
	v_add_f32_e32 v196, v196, v217

.Lat4_go:
	v_sub_f32_e32 v180, v200, v199
	v_sub_f32_e32 v198, v200, v201
	s_nop 0
	v_max3_f32 v217, v144, v145, v146
	v_max3_f32 v219, v160, v161, v162
	v_max3_f32 v221, v147, v148, v149
	v_max3_f32 v225, v163, v164, v165
	v_max3_f32 v223, v150, v151, v152
	v_max3_f32 v229, v166, v167, v168
	v_add_f32_e32 v144, v144, v180
	v_add_f32_e32 v160, v160, v198
	v_max3_f32 v217, v217, v221, v223
	v_exp_f32_e32 v144, v144
	v_exp_f32_e32 v160, v160
	v_max3_f32 v219, v219, v225, v229
	v_add_f32_e32 v145, v145, v180
	v_add_f32_e32 v161, v161, v198
	v_max3_f32 v221, v153, v154, v155
	v_exp_f32_e32 v145, v145
	v_exp_f32_e32 v161, v161
	v_max3_f32 v225, v169, v170, v171
	v_add_f32_e32 v146, v146, v180
	v_add_f32_e32 v162, v162, v198
	v_max3_f32 v223, v156, v157, v158
	v_exp_f32_e32 v146, v146
	v_exp_f32_e32 v162, v162
	v_max3_f32 v229, v172, v173, v174
	v_add_f32_e32 v147, v147, v180
	v_add_f32_e32 v163, v163, v198
	v_max3_f32 v221, v221, v223, v159
	v_exp_f32_e32 v147, v147
	v_exp_f32_e32 v163, v163
	v_max3_f32 v225, v225, v229, v175
	v_add_f32_e32 v148, v148, v180
	v_add_f32_e32 v164, v164, v198
	v_max_f32_e32 v217, v217, v221
	v_exp_f32_e32 v148, v148
	v_exp_f32_e32 v164, v164
	v_max_f32_e32 v219, v219, v225
	v_add_f32_e32 v149, v149, v180
	v_add_f32_e32 v165, v165, v198
	v_add_f32_e32 v221, v200, v217
	v_exp_f32_e32 v149, v149
	v_exp_f32_e32 v165, v165
	v_add_f32_e32 v225, v200, v219
	v_add_f32_e32 v150, v150, v180
	v_add_f32_e32 v166, v166, v198
	v_cmp_gt_f32_e32 vcc, v221, v227
	v_exp_f32_e32 v150, v150
	v_exp_f32_e32 v166, v166
	v_cmp_gt_f32_e64 s[0:1], v225, v215
	v_sub_f32_e32 v223, v221, v227
	v_sub_f32_e32 v229, v225, v215
	v_max_f32_e32 v223, v223, v229
	v_add_f32_e32 v223, 0x43080000, v223
	v_cmp_nlt_f32_e64 s[98:99], v223, 0
	v_add_f32_e32 v151, v151, v180
	v_add_f32_e32 v167, v167, v198
	v_exp_f32_e32 v151, v151
	v_exp_f32_e32 v167, v167
	v_add_f32_e32 v215, v144, v145
	v_add_f32_e32 v217, v160, v161
	v_add_f32_e32 v215, v215, v146
	v_add_f32_e32 v217, v217, v162
	v_add_f32_e32 v215, v215, v147
	v_add_f32_e32 v217, v217, v163
	v_add_f32_e32 v215, v215, v148
	v_add_f32_e32 v217, v217, v164
	v_add_f32_e32 v215, v215, v149
	v_add_f32_e32 v217, v217, v165
	v_add_f32_e32 v215, v215, v150
	v_add_f32_e32 v217, v217, v166
	v_add_f32_e32 v215, v215, v151
	v_add_f32_e32 v217, v217, v167
	v_cvt_pk_bf16_f32 v144, v144, v145
	v_cvt_pk_bf16_f32 v160, v160, v161
	v_cvt_pk_bf16_f32 v145, v146, v147
	v_cvt_pk_bf16_f32 v161, v162, v163
	v_cvt_pk_bf16_f32 v146, v148, v149
	v_cvt_pk_bf16_f32 v162, v164, v165
	v_cvt_pk_bf16_f32 v147, v150, v151
	v_cvt_pk_bf16_f32 v163, v166, v167
	ds_read_b64_tr_b16 v[148:149], v216 offset:20480
	ds_read_b64_tr_b16 v[150:151], v218 offset:20480
	ds_read_b64_tr_b16 v[164:165], v220 offset:20480
	ds_read_b64_tr_b16 v[166:167], v222 offset:20480
	s_or_b64 vcc, vcc, s[0:1]
	s_cbranch_vccnz .Lat4_redo
	s_cmp_eq_u64 s[98:99], 0
	s_cselect_b32 s51, 1, 0
	s_cbranch_scc1 .Lat4_skip
	s_waitcnt lgkmcnt(4)
	v_mfma_f32_32x32x16_bf16 v[112:127], v[202:205], v[144:147], v[112:127]
	v_add_f32_e32 v152, v152, v180
	v_add_f32_e32 v168, v168, v198
	v_exp_f32_e32 v152, v152
	v_exp_f32_e32 v168, v168
	v_mfma_f32_32x32x16_bf16 v[96:111], v[202:205], v[160:163], v[96:111]
	v_add_f32_e32 v153, v153, v180
	v_add_f32_e32 v169, v169, v198
	v_exp_f32_e32 v153, v153
	v_exp_f32_e32 v169, v169
	ds_read_b64_tr_b16 v[202:203], v224 offset:20480
	ds_read_b64_tr_b16 v[204:205], v226 offset:20480
	v_mfma_f32_32x32x16_bf16 v[64:79], v[244:247], v[144:147], v[64:79]
	v_add_f32_e32 v154, v154, v180
	v_add_f32_e32 v170, v170, v198
	v_exp_f32_e32 v154, v154
	v_exp_f32_e32 v170, v170
	v_mfma_f32_32x32x16_bf16 v[80:95], v[244:247], v[160:163], v[80:95]
	v_add_f32_e32 v155, v155, v180
	v_add_f32_e32 v171, v171, v198
	v_exp_f32_e32 v155, v155
	v_exp_f32_e32 v171, v171
	ds_read_b64_tr_b16 v[244:245], v228 offset:20480
	ds_read_b64_tr_b16 v[246:247], v230 offset:20480
	v_mfma_f32_32x32x16_bf16 v[32:47], v[248:251], v[144:147], v[32:47]
	v_add_f32_e32 v156, v156, v180
	v_add_f32_e32 v172, v172, v198
	v_exp_f32_e32 v156, v156
	v_exp_f32_e32 v172, v172
	v_mfma_f32_32x32x16_bf16 v[48:63], v[248:251], v[160:163], v[48:63]
	v_add_f32_e32 v157, v157, v180
	v_add_f32_e32 v173, v173, v198
	v_exp_f32_e32 v157, v157
	v_exp_f32_e32 v173, v173
	v_mfma_f32_32x32x16_bf16 v[0:15], v[252:255], v[144:147], v[0:15]
	v_add_f32_e32 v158, v158, v180
	v_add_f32_e32 v174, v174, v198
	v_exp_f32_e32 v158, v158
	v_exp_f32_e32 v174, v174
	v_mfma_f32_32x32x16_bf16 v[16:31], v[252:255], v[160:163], v[16:31]
	v_add_f32_e32 v159, v159, v180
	v_add_f32_e32 v175, v175, v198
	v_exp_f32_e32 v159, v159
	v_exp_f32_e32 v175, v175
	v_cvt_pk_bf16_f32 v248, v152, v153
	v_cvt_pk_bf16_f32 v252, v168, v169
	v_cvt_pk_bf16_f32 v249, v154, v155
	v_cvt_pk_bf16_f32 v253, v170, v171
	v_cvt_pk_bf16_f32 v250, v156, v157
	v_cvt_pk_bf16_f32 v254, v172, v173
	v_cvt_pk_bf16_f32 v251, v158, v159
	v_cvt_pk_bf16_f32 v255, v174, v175
	s_nop 0
	s_waitcnt lgkmcnt(6)
	v_mfma_f32_32x32x16_bf16 v[112:127], v[148:151], v[248:251], v[112:127]
	v_add_f32_e32 v215, v215, v152
	v_add_f32_e32 v217, v217, v168
	v_mfma_f32_32x32x16_bf16 v[96:111], v[148:151], v[252:255], v[96:111]
	v_add_f32_e32 v215, v215, v153
	v_add_f32_e32 v217, v217, v169
	v_add_f32_e32 v215, v215, v154
	s_waitcnt lgkmcnt(4)
	v_mfma_f32_32x32x16_bf16 v[64:79], v[164:167], v[248:251], v[64:79]
	v_add_f32_e32 v217, v217, v170
	v_add_f32_e32 v215, v215, v155
	v_mfma_f32_32x32x16_bf16 v[80:95], v[164:167], v[252:255], v[80:95]
	v_add_f32_e32 v217, v217, v171
	v_add_f32_e32 v215, v215, v156
	v_add_f32_e32 v217, v217, v172
	s_waitcnt lgkmcnt(2)
	v_mfma_f32_32x32x16_bf16 v[32:47], v[202:205], v[248:251], v[32:47]
	v_add_f32_e32 v215, v215, v157
	v_add_f32_e32 v217, v217, v173
	v_mfma_f32_32x32x16_bf16 v[48:63], v[202:205], v[252:255], v[48:63]
	v_add_f32_e32 v215, v215, v158
	v_add_f32_e32 v217, v217, v174
	v_add_f32_e32 v215, v215, v159
	s_waitcnt lgkmcnt(0)
	v_mfma_f32_32x32x16_bf16 v[0:15], v[244:247], v[248:251], v[0:15]
	v_add_f32_e32 v217, v217, v175
	v_add_f32_e32 v197, v197, v215
	v_mfma_f32_32x32x16_bf16 v[16:31], v[244:247], v[252:255], v[16:31]
	v_add_f32_e32 v196, v196, v217

.Lat5_go:
	v_sub_f32_e32 v180, v200, v199
	v_sub_f32_e32 v198, v200, v201
	s_nop 0
	v_max3_f32 v217, v144, v145, v146
	v_max3_f32 v219, v160, v161, v162
	v_max3_f32 v221, v147, v148, v149
	v_max3_f32 v225, v163, v164, v165
	v_max3_f32 v223, v150, v151, v152
	v_max3_f32 v229, v166, v167, v168
	v_add_f32_e32 v144, v144, v180
	v_add_f32_e32 v160, v160, v198
	v_max3_f32 v217, v217, v221, v223
	v_exp_f32_e32 v144, v144
	v_exp_f32_e32 v160, v160
	v_max3_f32 v219, v219, v225, v229
	v_add_f32_e32 v145, v145, v180
	v_add_f32_e32 v161, v161, v198
	v_max3_f32 v221, v153, v154, v155
	v_exp_f32_e32 v145, v145
	v_exp_f32_e32 v161, v161
	v_max3_f32 v225, v169, v170, v171
	v_add_f32_e32 v146, v146, v180
	v_add_f32_e32 v162, v162, v198
	v_max3_f32 v223, v156, v157, v158
	v_exp_f32_e32 v146, v146
	v_exp_f32_e32 v162, v162
	v_max3_f32 v229, v172, v173, v174
	v_add_f32_e32 v147, v147, v180
	v_add_f32_e32 v163, v163, v198
	v_max3_f32 v221, v221, v223, v159
	v_exp_f32_e32 v147, v147
	v_exp_f32_e32 v163, v163
	v_max3_f32 v225, v225, v229, v175
	v_add_f32_e32 v148, v148, v180
	v_add_f32_e32 v164, v164, v198
	v_max_f32_e32 v217, v217, v221
	v_exp_f32_e32 v148, v148
	v_exp_f32_e32 v164, v164
	v_max_f32_e32 v219, v219, v225
	v_add_f32_e32 v149, v149, v180
	v_add_f32_e32 v165, v165, v198
	v_add_f32_e32 v221, v200, v217
	v_exp_f32_e32 v149, v149
	v_exp_f32_e32 v165, v165
	v_add_f32_e32 v225, v200, v219
	v_add_f32_e32 v150, v150, v180
	v_add_f32_e32 v166, v166, v198
	v_cmp_gt_f32_e32 vcc, v221, v227
	v_exp_f32_e32 v150, v150
	v_exp_f32_e32 v166, v166
	v_cmp_gt_f32_e64 s[0:1], v225, v215
	v_sub_f32_e32 v223, v221, v227
	v_sub_f32_e32 v229, v225, v215
	v_max_f32_e32 v223, v223, v229
	v_add_f32_e32 v223, 0x43080000, v223
	v_cmp_nlt_f32_e64 s[98:99], v223, 0
	v_add_f32_e32 v151, v151, v180
	v_add_f32_e32 v167, v167, v198
	v_exp_f32_e32 v151, v151
	v_exp_f32_e32 v167, v167
	v_add_f32_e32 v215, v144, v145
	v_add_f32_e32 v217, v160, v161
	v_add_f32_e32 v215, v215, v146
	v_add_f32_e32 v217, v217, v162
	v_add_f32_e32 v215, v215, v147
	v_add_f32_e32 v217, v217, v163
	v_add_f32_e32 v215, v215, v148
	v_add_f32_e32 v217, v217, v164
	v_add_f32_e32 v215, v215, v149
	v_add_f32_e32 v217, v217, v165
	v_add_f32_e32 v215, v215, v150
	v_add_f32_e32 v217, v217, v166
	v_add_f32_e32 v215, v215, v151
	v_add_f32_e32 v217, v217, v167
	v_cvt_pk_bf16_f32 v144, v144, v145
	v_cvt_pk_bf16_f32 v160, v160, v161
	v_cvt_pk_bf16_f32 v145, v146, v147
	v_cvt_pk_bf16_f32 v161, v162, v163
	v_cvt_pk_bf16_f32 v146, v148, v149
	v_cvt_pk_bf16_f32 v162, v164, v165
	v_cvt_pk_bf16_f32 v147, v150, v151
	v_cvt_pk_bf16_f32 v163, v166, v167
	ds_read_b64_tr_b16 v[148:149], v216 offset:45056
	ds_read_b64_tr_b16 v[150:151], v218 offset:45056
	ds_read_b64_tr_b16 v[164:165], v220 offset:45056
	ds_read_b64_tr_b16 v[166:167], v222 offset:45056
	s_or_b64 vcc, vcc, s[0:1]
	s_cbranch_vccnz .Lat5_redo
	s_cmp_eq_u64 s[98:99], 0
	s_cselect_b32 s51, 1, 0
	s_cbranch_scc1 .Lat5_skip
	s_waitcnt lgkmcnt(4)
	v_mfma_f32_32x32x16_bf16 v[112:127], v[202:205], v[144:147], v[112:127]
	v_add_f32_e32 v152, v152, v180
	v_add_f32_e32 v168, v168, v198
	v_exp_f32_e32 v152, v152
	v_exp_f32_e32 v168, v168
	v_mfma_f32_32x32x16_bf16 v[96:111], v[202:205], v[160:163], v[96:111]
	v_add_f32_e32 v153, v153, v180
	v_add_f32_e32 v169, v169, v198
	v_exp_f32_e32 v153, v153
	v_exp_f32_e32 v169, v169
	ds_read_b64_tr_b16 v[202:203], v224 offset:45056
	ds_read_b64_tr_b16 v[204:205], v226 offset:45056
	v_mfma_f32_32x32x16_bf16 v[64:79], v[244:247], v[144:147], v[64:79]
	v_add_f32_e32 v154, v154, v180
	v_add_f32_e32 v170, v170, v198
	v_exp_f32_e32 v154, v154
	v_exp_f32_e32 v170, v170
	v_mfma_f32_32x32x16_bf16 v[80:95], v[244:247], v[160:163], v[80:95]
	v_add_f32_e32 v155, v155, v180
	v_add_f32_e32 v171, v171, v198
	v_exp_f32_e32 v155, v155
	v_exp_f32_e32 v171, v171
	ds_read_b64_tr_b16 v[244:245], v228 offset:45056
	ds_read_b64_tr_b16 v[246:247], v230 offset:45056
	v_mfma_f32_32x32x16_bf16 v[32:47], v[248:251], v[144:147], v[32:47]
	v_add_f32_e32 v156, v156, v180
	v_add_f32_e32 v172, v172, v198
	v_exp_f32_e32 v156, v156
	v_exp_f32_e32 v172, v172
	v_mfma_f32_32x32x16_bf16 v[48:63], v[248:251], v[160:163], v[48:63]
	v_add_f32_e32 v157, v157, v180
	v_add_f32_e32 v173, v173, v198
	v_exp_f32_e32 v157, v157
	v_exp_f32_e32 v173, v173
	v_mfma_f32_32x32x16_bf16 v[0:15], v[252:255], v[144:147], v[0:15]
	v_add_f32_e32 v158, v158, v180
	v_add_f32_e32 v174, v174, v198
	v_exp_f32_e32 v158, v158
	v_exp_f32_e32 v174, v174
	v_mfma_f32_32x32x16_bf16 v[16:31], v[252:255], v[160:163], v[16:31]
	v_add_f32_e32 v159, v159, v180
	v_add_f32_e32 v175, v175, v198
	v_exp_f32_e32 v159, v159
	v_exp_f32_e32 v175, v175
	v_cvt_pk_bf16_f32 v248, v152, v153
	v_cvt_pk_bf16_f32 v252, v168, v169
	v_cvt_pk_bf16_f32 v249, v154, v155
	v_cvt_pk_bf16_f32 v253, v170, v171
	v_cvt_pk_bf16_f32 v250, v156, v157
	v_cvt_pk_bf16_f32 v254, v172, v173
	v_cvt_pk_bf16_f32 v251, v158, v159
	v_cvt_pk_bf16_f32 v255, v174, v175
	s_nop 0
	s_waitcnt lgkmcnt(6)
	v_mfma_f32_32x32x16_bf16 v[112:127], v[148:151], v[248:251], v[112:127]
	v_add_f32_e32 v215, v215, v152
	v_add_f32_e32 v217, v217, v168
	v_mfma_f32_32x32x16_bf16 v[96:111], v[148:151], v[252:255], v[96:111]
	v_add_f32_e32 v215, v215, v153
	v_add_f32_e32 v217, v217, v169
	v_add_f32_e32 v215, v215, v154
	s_waitcnt lgkmcnt(4)
	v_mfma_f32_32x32x16_bf16 v[64:79], v[164:167], v[248:251], v[64:79]
	v_add_f32_e32 v217, v217, v170
	v_add_f32_e32 v215, v215, v155
	v_mfma_f32_32x32x16_bf16 v[80:95], v[164:167], v[252:255], v[80:95]
	v_add_f32_e32 v217, v217, v171
	v_add_f32_e32 v215, v215, v156
	v_add_f32_e32 v217, v217, v172
	s_waitcnt lgkmcnt(2)
	v_mfma_f32_32x32x16_bf16 v[32:47], v[202:205], v[248:251], v[32:47]
	v_add_f32_e32 v215, v215, v157
	v_add_f32_e32 v217, v217, v173
	v_mfma_f32_32x32x16_bf16 v[48:63], v[202:205], v[252:255], v[48:63]
	v_add_f32_e32 v215, v215, v158
	v_add_f32_e32 v217, v217, v174
	v_add_f32_e32 v215, v215, v159
	s_waitcnt lgkmcnt(0)
	v_mfma_f32_32x32x16_bf16 v[0:15], v[244:247], v[248:251], v[0:15]
	v_add_f32_e32 v217, v217, v175
	v_add_f32_e32 v197, v197, v215
	v_mfma_f32_32x32x16_bf16 v[16:31], v[244:247], v[252:255], v[16:31]
	v_add_f32_e32 v196, v196, v217

.Lat6_go:
	v_sub_f32_e32 v180, v200, v199
	v_sub_f32_e32 v198, v200, v201
	s_nop 0
	v_max3_f32 v217, v144, v145, v146
	v_max3_f32 v219, v160, v161, v162
	v_max3_f32 v221, v147, v148, v149
	v_max3_f32 v225, v163, v164, v165
	v_max3_f32 v223, v150, v151, v152
	v_max3_f32 v229, v166, v167, v168
	v_add_f32_e32 v144, v144, v180
	v_add_f32_e32 v160, v160, v198
	v_max3_f32 v217, v217, v221, v223
	v_exp_f32_e32 v144, v144
	v_exp_f32_e32 v160, v160
	v_max3_f32 v219, v219, v225, v229
	v_add_f32_e32 v145, v145, v180
	v_add_f32_e32 v161, v161, v198
	v_max3_f32 v221, v153, v154, v155
	v_exp_f32_e32 v145, v145
	v_exp_f32_e32 v161, v161
	v_max3_f32 v225, v169, v170, v171
	v_add_f32_e32 v146, v146, v180
	v_add_f32_e32 v162, v162, v198
	v_max3_f32 v223, v156, v157, v158
	v_exp_f32_e32 v146, v146
	v_exp_f32_e32 v162, v162
	v_max3_f32 v229, v172, v173, v174
	v_add_f32_e32 v147, v147, v180
	v_add_f32_e32 v163, v163, v198
	v_max3_f32 v221, v221, v223, v159
	v_exp_f32_e32 v147, v147
	v_exp_f32_e32 v163, v163
	v_max3_f32 v225, v225, v229, v175
	v_add_f32_e32 v148, v148, v180
	v_add_f32_e32 v164, v164, v198
	v_max_f32_e32 v217, v217, v221
	v_exp_f32_e32 v148, v148
	v_exp_f32_e32 v164, v164
	v_max_f32_e32 v219, v219, v225
	v_add_f32_e32 v149, v149, v180
	v_add_f32_e32 v165, v165, v198
	v_add_f32_e32 v221, v200, v217
	v_exp_f32_e32 v149, v149
	v_exp_f32_e32 v165, v165
	v_add_f32_e32 v225, v200, v219
	v_add_f32_e32 v150, v150, v180
	v_add_f32_e32 v166, v166, v198
	v_cmp_gt_f32_e32 vcc, v221, v227
	v_exp_f32_e32 v150, v150
	v_exp_f32_e32 v166, v166
	v_cmp_gt_f32_e64 s[0:1], v225, v215
	v_sub_f32_e32 v223, v221, v227
	v_sub_f32_e32 v229, v225, v215
	v_max_f32_e32 v223, v223, v229
	v_add_f32_e32 v223, 0x43080000, v223
	v_cmp_nlt_f32_e64 s[98:99], v223, 0
	v_add_f32_e32 v151, v151, v180
	v_add_f32_e32 v167, v167, v198
	v_exp_f32_e32 v151, v151
	v_exp_f32_e32 v167, v167
	v_add_f32_e32 v215, v144, v145
	v_add_f32_e32 v217, v160, v161
	v_add_f32_e32 v215, v215, v146
	v_add_f32_e32 v217, v217, v162
	v_add_f32_e32 v215, v215, v147
	v_add_f32_e32 v217, v217, v163
	v_add_f32_e32 v215, v215, v148
	v_add_f32_e32 v217, v217, v164
	v_add_f32_e32 v215, v215, v149
	v_add_f32_e32 v217, v217, v165
	v_add_f32_e32 v215, v215, v150
	v_add_f32_e32 v217, v217, v166
	v_add_f32_e32 v215, v215, v151
	v_add_f32_e32 v217, v217, v167
	v_cvt_pk_bf16_f32 v144, v144, v145
	v_cvt_pk_bf16_f32 v160, v160, v161
	v_cvt_pk_bf16_f32 v145, v146, v147
	v_cvt_pk_bf16_f32 v161, v162, v163
	v_cvt_pk_bf16_f32 v146, v148, v149
	v_cvt_pk_bf16_f32 v162, v164, v165
	v_cvt_pk_bf16_f32 v147, v150, v151
	v_cvt_pk_bf16_f32 v163, v166, v167
	ds_read_b64_tr_b16 v[148:149], v216 offset:36864
	ds_read_b64_tr_b16 v[150:151], v218 offset:36864
	ds_read_b64_tr_b16 v[164:165], v220 offset:36864
	ds_read_b64_tr_b16 v[166:167], v222 offset:36864
	s_or_b64 vcc, vcc, s[0:1]
	s_cbranch_vccnz .Lat6_redo
	s_cmp_eq_u64 s[98:99], 0
	s_cselect_b32 s51, 1, 0
	s_cbranch_scc1 .Lat6_skip
	s_waitcnt lgkmcnt(4)
	v_mfma_f32_32x32x16_bf16 v[112:127], v[202:205], v[144:147], v[112:127]
	v_add_f32_e32 v152, v152, v180
	v_add_f32_e32 v168, v168, v198
	v_exp_f32_e32 v152, v152
	v_exp_f32_e32 v168, v168
	v_mfma_f32_32x32x16_bf16 v[96:111], v[202:205], v[160:163], v[96:111]
	v_add_f32_e32 v153, v153, v180
	v_add_f32_e32 v169, v169, v198
	v_exp_f32_e32 v153, v153
	v_exp_f32_e32 v169, v169
	ds_read_b64_tr_b16 v[202:203], v224 offset:36864
	ds_read_b64_tr_b16 v[204:205], v226 offset:36864
	v_mfma_f32_32x32x16_bf16 v[64:79], v[244:247], v[144:147], v[64:79]
	v_add_f32_e32 v154, v154, v180
	v_add_f32_e32 v170, v170, v198
	v_exp_f32_e32 v154, v154
	v_exp_f32_e32 v170, v170
	v_mfma_f32_32x32x16_bf16 v[80:95], v[244:247], v[160:163], v[80:95]
	v_add_f32_e32 v155, v155, v180
	v_add_f32_e32 v171, v171, v198
	v_exp_f32_e32 v155, v155
	v_exp_f32_e32 v171, v171
	ds_read_b64_tr_b16 v[244:245], v228 offset:36864
	ds_read_b64_tr_b16 v[246:247], v230 offset:36864
	v_mfma_f32_32x32x16_bf16 v[32:47], v[248:251], v[144:147], v[32:47]
	v_add_f32_e32 v156, v156, v180
	v_add_f32_e32 v172, v172, v198
	v_exp_f32_e32 v156, v156
	v_exp_f32_e32 v172, v172
	v_mfma_f32_32x32x16_bf16 v[48:63], v[248:251], v[160:163], v[48:63]
	v_add_f32_e32 v157, v157, v180
	v_add_f32_e32 v173, v173, v198
	v_exp_f32_e32 v157, v157
	v_exp_f32_e32 v173, v173
	v_mfma_f32_32x32x16_bf16 v[0:15], v[252:255], v[144:147], v[0:15]
	v_add_f32_e32 v158, v158, v180
	v_add_f32_e32 v174, v174, v198
	v_exp_f32_e32 v158, v158
	v_exp_f32_e32 v174, v174
	v_mfma_f32_32x32x16_bf16 v[16:31], v[252:255], v[160:163], v[16:31]
	v_add_f32_e32 v159, v159, v180
	v_add_f32_e32 v175, v175, v198
	v_exp_f32_e32 v159, v159
	v_exp_f32_e32 v175, v175
	v_cvt_pk_bf16_f32 v248, v152, v153
	v_cvt_pk_bf16_f32 v252, v168, v169
	v_cvt_pk_bf16_f32 v249, v154, v155
	v_cvt_pk_bf16_f32 v253, v170, v171
	v_cvt_pk_bf16_f32 v250, v156, v157
	v_cvt_pk_bf16_f32 v254, v172, v173
	v_cvt_pk_bf16_f32 v251, v158, v159
	v_cvt_pk_bf16_f32 v255, v174, v175
	s_nop 0
	s_waitcnt lgkmcnt(6)
	v_mfma_f32_32x32x16_bf16 v[112:127], v[148:151], v[248:251], v[112:127]
	v_add_f32_e32 v215, v215, v152
	v_add_f32_e32 v217, v217, v168
	v_mfma_f32_32x32x16_bf16 v[96:111], v[148:151], v[252:255], v[96:111]
	v_add_f32_e32 v215, v215, v153
	v_add_f32_e32 v217, v217, v169
	v_add_f32_e32 v215, v215, v154
	s_waitcnt lgkmcnt(4)
	v_mfma_f32_32x32x16_bf16 v[64:79], v[164:167], v[248:251], v[64:79]
	v_add_f32_e32 v217, v217, v170
	v_add_f32_e32 v215, v215, v155
	v_mfma_f32_32x32x16_bf16 v[80:95], v[164:167], v[252:255], v[80:95]
	v_add_f32_e32 v217, v217, v171
	v_add_f32_e32 v215, v215, v156
	v_add_f32_e32 v217, v217, v172
	s_waitcnt lgkmcnt(2)
	v_mfma_f32_32x32x16_bf16 v[32:47], v[202:205], v[248:251], v[32:47]
	v_add_f32_e32 v215, v215, v157
	v_add_f32_e32 v217, v217, v173
	v_mfma_f32_32x32x16_bf16 v[48:63], v[202:205], v[252:255], v[48:63]
	v_add_f32_e32 v215, v215, v158
	v_add_f32_e32 v217, v217, v174
	v_add_f32_e32 v215, v215, v159
	s_waitcnt lgkmcnt(0)
	v_mfma_f32_32x32x16_bf16 v[0:15], v[244:247], v[248:251], v[0:15]
	v_add_f32_e32 v217, v217, v175
	v_add_f32_e32 v197, v197, v215
	v_mfma_f32_32x32x16_bf16 v[16:31], v[244:247], v[252:255], v[16:31]
	v_add_f32_e32 v196, v196, v217

.Lat1_probe:
	ds_read_b128 v[160:163], v237 offset:8192
	ds_read_b128 v[164:167], v189
	ds_read_b128 v[202:205], v235 offset:8192
	ds_read_b128 v[244:247], v189 offset:4096
	ds_read_b128 v[248:251], v236 offset:8192
	ds_read_b128 v[252:255], v189 offset:1024
	s_waitcnt lgkmcnt(4)
	v_mfma_f32_32x32x16_bf16 v[144:159], v[160:163], v[164:167], v[128:143]
	s_waitcnt lgkmcnt(2)
	v_mfma_f32_32x32x16_bf16 v[160:175], v[202:205], v[244:247], v[128:143]
	ds_read_b128 v[202:205], v234 offset:8192
	ds_read_b128 v[244:247], v189 offset:5120
	v_add_u32_e32 v215, s40, v185
	v_add_u32_e32 v215, 0xe0, v215
	v_cvt_f32_i32_e32 v215, v215
	v_add_f32_e32 v227, 0x41000000, v199
	v_mul_f32_e32 v200, v184, v215
	v_add_f32_e32 v215, 0x41000000, v201
	s_waitcnt lgkmcnt(2)
	v_mfma_f32_32x32x16_bf16 v[144:159], v[248:251], v[252:255], v[144:159]
	ds_read_b128 v[248:251], v241 offset:8192
	ds_read_b128 v[252:255], v189 offset:2048
	s_waitcnt lgkmcnt(2)
	v_mfma_f32_32x32x16_bf16 v[160:175], v[202:205], v[244:247], v[160:175]
	ds_read_b128 v[202:205], v239 offset:8192
	ds_read_b128 v[244:247], v189 offset:6144
	s_waitcnt lgkmcnt(2)
	v_mfma_f32_32x32x16_bf16 v[144:159], v[248:251], v[252:255], v[144:159]
	ds_read_b128 v[248:251], v240 offset:8192
	ds_read_b128 v[252:255], v189 offset:3072
	s_waitcnt lgkmcnt(2)
	v_mfma_f32_32x32x16_bf16 v[160:175], v[202:205], v[244:247], v[160:175]
	ds_read_b128 v[202:205], v238 offset:8192
	ds_read_b128 v[244:247], v189 offset:7168
	s_waitcnt lgkmcnt(2)
	v_mfma_f32_32x32x16_bf16 v[144:159], v[248:251], v[252:255], v[144:159]
	s_waitcnt lgkmcnt(0)
	v_mfma_f32_32x32x16_bf16 v[160:175], v[202:205], v[244:247], v[160:175]
	s_nop 7
	s_nop 7
	v_max3_f32 v217, v144, v145, v146
	v_max3_f32 v219, v160, v161, v162
	v_max3_f32 v221, v147, v148, v149
	v_max3_f32 v225, v163, v164, v165
	v_max3_f32 v223, v150, v151, v152
	v_max3_f32 v229, v166, v167, v168
	v_max3_f32 v217, v217, v221, v223
	v_max3_f32 v219, v219, v225, v229
	v_max3_f32 v221, v153, v154, v155
	v_max3_f32 v225, v169, v170, v171
	v_max3_f32 v223, v156, v157, v158
	v_max3_f32 v229, v172, v173, v174
	v_max3_f32 v221, v221, v223, v159
	v_max3_f32 v225, v225, v229, v175
	v_max_f32_e32 v217, v217, v221
	v_max_f32_e32 v219, v219, v225
	v_add_f32_e32 v221, v200, v217
	v_add_f32_e32 v225, v200, v219
	v_sub_f32_e32 v223, v221, v227
	v_sub_f32_e32 v229, v225, v215
	v_max_f32_e32 v223, v223, v229
	v_add_f32_e32 v223, 0x43080000, v223
	v_cmp_nlt_f32_e64 s[98:99], v223, 0
	s_nop 3
	s_cmp_eq_u64 s[98:99], 0
	s_cbranch_scc1 .Lat1_skip
	s_mov_b32 s51, 0
	s_branch .Lat1_redo
.Lat2_probe:
	ds_read_b128 v[160:163], v237
	ds_read_b128 v[164:167], v189
	ds_read_b128 v[202:205], v235
	ds_read_b128 v[244:247], v189 offset:4096
	ds_read_b128 v[248:251], v236
	ds_read_b128 v[252:255], v189 offset:1024
	s_waitcnt lgkmcnt(4)
	v_mfma_f32_32x32x16_bf16 v[144:159], v[160:163], v[164:167], v[128:143]
	s_waitcnt lgkmcnt(2)
	v_mfma_f32_32x32x16_bf16 v[160:175], v[202:205], v[244:247], v[128:143]
	ds_read_b128 v[202:205], v234
	ds_read_b128 v[244:247], v189 offset:5120
	v_add_u32_e32 v215, s40, v185
	v_add_u32_e32 v215, 0xc0, v215
	v_cvt_f32_i32_e32 v215, v215
	v_add_f32_e32 v227, 0x41000000, v199
	v_mul_f32_e32 v200, v184, v215
	v_add_f32_e32 v215, 0x41000000, v201
	s_waitcnt lgkmcnt(2)
	v_mfma_f32_32x32x16_bf16 v[144:159], v[248:251], v[252:255], v[144:159]
	ds_read_b128 v[248:251], v241
	ds_read_b128 v[252:255], v189 offset:2048
	s_waitcnt lgkmcnt(2)
	v_mfma_f32_32x32x16_bf16 v[160:175], v[202:205], v[244:247], v[160:175]
	ds_read_b128 v[202:205], v239
	ds_read_b128 v[244:247], v189 offset:6144
	s_waitcnt lgkmcnt(2)
	v_mfma_f32_32x32x16_bf16 v[144:159], v[248:251], v[252:255], v[144:159]
	ds_read_b128 v[248:251], v240
	ds_read_b128 v[252:255], v189 offset:3072
	s_waitcnt lgkmcnt(2)
	v_mfma_f32_32x32x16_bf16 v[160:175], v[202:205], v[244:247], v[160:175]
	ds_read_b128 v[202:205], v238
	ds_read_b128 v[244:247], v189 offset:7168
	s_waitcnt lgkmcnt(2)
	v_mfma_f32_32x32x16_bf16 v[144:159], v[248:251], v[252:255], v[144:159]
	s_waitcnt lgkmcnt(0)
	v_mfma_f32_32x32x16_bf16 v[160:175], v[202:205], v[244:247], v[160:175]
	s_nop 7
	s_nop 7
	v_max3_f32 v217, v144, v145, v146
	v_max3_f32 v219, v160, v161, v162
	v_max3_f32 v221, v147, v148, v149
	v_max3_f32 v225, v163, v164, v165
	v_max3_f32 v223, v150, v151, v152
	v_max3_f32 v229, v166, v167, v168
	v_max3_f32 v217, v217, v221, v223
	v_max3_f32 v219, v219, v225, v229
	v_max3_f32 v221, v153, v154, v155
	v_max3_f32 v225, v169, v170, v171
	v_max3_f32 v223, v156, v157, v158
	v_max3_f32 v229, v172, v173, v174
	v_max3_f32 v221, v221, v223, v159
	v_max3_f32 v225, v225, v229, v175
	v_max_f32_e32 v217, v217, v221
	v_max_f32_e32 v219, v219, v225
	v_add_f32_e32 v221, v200, v217
	v_add_f32_e32 v225, v200, v219
	v_sub_f32_e32 v223, v221, v227
	v_sub_f32_e32 v229, v225, v215
	v_max_f32_e32 v223, v223, v229
	v_add_f32_e32 v223, 0x43080000, v223
	v_cmp_nlt_f32_e64 s[98:99], v223, 0
	s_nop 3
	s_cmp_eq_u64 s[98:99], 0
	s_cbranch_scc1 .Lat2_skip
	s_mov_b32 s51, 0
	s_branch .Lat2_redo
.Lat3_probe:
	ds_read_b128 v[160:163], v237 offset:24576
	ds_read_b128 v[164:167], v189
	ds_read_b128 v[202:205], v235 offset:24576
	ds_read_b128 v[244:247], v189 offset:4096
	ds_read_b128 v[248:251], v236 offset:24576
	ds_read_b128 v[252:255], v189 offset:1024
	s_waitcnt lgkmcnt(4)
	v_mfma_f32_32x32x16_bf16 v[144:159], v[160:163], v[164:167], v[128:143]
	s_waitcnt lgkmcnt(2)
	v_mfma_f32_32x32x16_bf16 v[160:175], v[202:205], v[244:247], v[128:143]
	ds_read_b128 v[202:205], v234 offset:24576
	ds_read_b128 v[244:247], v189 offset:5120
	v_add_u32_e32 v215, s40, v185
	v_add_u32_e32 v215, 0xa0, v215
	v_cvt_f32_i32_e32 v215, v215
	v_add_f32_e32 v227, 0x41000000, v199
	v_mul_f32_e32 v200, v184, v215
	v_add_f32_e32 v215, 0x41000000, v201
	s_waitcnt lgkmcnt(2)
	v_mfma_f32_32x32x16_bf16 v[144:159], v[248:251], v[252:255], v[144:159]
	ds_read_b128 v[248:251], v241 offset:24576
	ds_read_b128 v[252:255], v189 offset:2048
	s_waitcnt lgkmcnt(2)
	v_mfma_f32_32x32x16_bf16 v[160:175], v[202:205], v[244:247], v[160:175]
	ds_read_b128 v[202:205], v239 offset:24576
	ds_read_b128 v[244:247], v189 offset:6144
	s_waitcnt lgkmcnt(2)
	v_mfma_f32_32x32x16_bf16 v[144:159], v[248:251], v[252:255], v[144:159]
	ds_read_b128 v[248:251], v240 offset:24576
	ds_read_b128 v[252:255], v189 offset:3072
	s_waitcnt lgkmcnt(2)
	v_mfma_f32_32x32x16_bf16 v[160:175], v[202:205], v[244:247], v[160:175]
	ds_read_b128 v[202:205], v238 offset:24576
	ds_read_b128 v[244:247], v189 offset:7168
	s_waitcnt lgkmcnt(2)
	v_mfma_f32_32x32x16_bf16 v[144:159], v[248:251], v[252:255], v[144:159]
	s_waitcnt lgkmcnt(0)
	v_mfma_f32_32x32x16_bf16 v[160:175], v[202:205], v[244:247], v[160:175]
	s_nop 7
	s_nop 7
	v_max3_f32 v217, v144, v145, v146
	v_max3_f32 v219, v160, v161, v162
	v_max3_f32 v221, v147, v148, v149
	v_max3_f32 v225, v163, v164, v165
	v_max3_f32 v223, v150, v151, v152
	v_max3_f32 v229, v166, v167, v168
	v_max3_f32 v217, v217, v221, v223
	v_max3_f32 v219, v219, v225, v229
	v_max3_f32 v221, v153, v154, v155
	v_max3_f32 v225, v169, v170, v171
	v_max3_f32 v223, v156, v157, v158
	v_max3_f32 v229, v172, v173, v174
	v_max3_f32 v221, v221, v223, v159
	v_max3_f32 v225, v225, v229, v175
	v_max_f32_e32 v217, v217, v221
	v_max_f32_e32 v219, v219, v225
	v_add_f32_e32 v221, v200, v217
	v_add_f32_e32 v225, v200, v219
	v_sub_f32_e32 v223, v221, v227
	v_sub_f32_e32 v229, v225, v215
	v_max_f32_e32 v223, v223, v229
	v_add_f32_e32 v223, 0x43080000, v223
	v_cmp_nlt_f32_e64 s[98:99], v223, 0
	s_nop 3
	s_cmp_eq_u64 s[98:99], 0
	s_cbranch_scc1 .Lat3_skip
	s_mov_b32 s51, 0
	s_branch .Lat3_redo
.Lat4_probe:
	ds_read_b128 v[160:163], v237 offset:16384
	ds_read_b128 v[164:167], v189
	ds_read_b128 v[202:205], v235 offset:16384
	ds_read_b128 v[244:247], v189 offset:4096
	ds_read_b128 v[248:251], v236 offset:16384
	ds_read_b128 v[252:255], v189 offset:1024
	s_waitcnt lgkmcnt(4)
	v_mfma_f32_32x32x16_bf16 v[144:159], v[160:163], v[164:167], v[128:143]
	s_waitcnt lgkmcnt(2)
	v_mfma_f32_32x32x16_bf16 v[160:175], v[202:205], v[244:247], v[128:143]
	ds_read_b128 v[202:205], v234 offset:16384
	ds_read_b128 v[244:247], v189 offset:5120
	v_add_u32_e32 v215, s40, v185
	v_add_u32_e32 v215, 0x80, v215
	v_cvt_f32_i32_e32 v215, v215
	v_add_f32_e32 v227, 0x41000000, v199
	v_mul_f32_e32 v200, v184, v215
	v_add_f32_e32 v215, 0x41000000, v201
	s_waitcnt lgkmcnt(2)
	v_mfma_f32_32x32x16_bf16 v[144:159], v[248:251], v[252:255], v[144:159]
	ds_read_b128 v[248:251], v241 offset:16384
	ds_read_b128 v[252:255], v189 offset:2048
	s_waitcnt lgkmcnt(2)
	v_mfma_f32_32x32x16_bf16 v[160:175], v[202:205], v[244:247], v[160:175]
	ds_read_b128 v[202:205], v239 offset:16384
	ds_read_b128 v[244:247], v189 offset:6144
	s_waitcnt lgkmcnt(2)
	v_mfma_f32_32x32x16_bf16 v[144:159], v[248:251], v[252:255], v[144:159]
	ds_read_b128 v[248:251], v240 offset:16384
	ds_read_b128 v[252:255], v189 offset:3072
	s_waitcnt lgkmcnt(2)
	v_mfma_f32_32x32x16_bf16 v[160:175], v[202:205], v[244:247], v[160:175]
	ds_read_b128 v[202:205], v238 offset:16384
	ds_read_b128 v[244:247], v189 offset:7168
	s_waitcnt lgkmcnt(2)
	v_mfma_f32_32x32x16_bf16 v[144:159], v[248:251], v[252:255], v[144:159]
	s_waitcnt lgkmcnt(0)
	v_mfma_f32_32x32x16_bf16 v[160:175], v[202:205], v[244:247], v[160:175]
	s_nop 7
	s_nop 7
	v_max3_f32 v217, v144, v145, v146
	v_max3_f32 v219, v160, v161, v162
	v_max3_f32 v221, v147, v148, v149
	v_max3_f32 v225, v163, v164, v165
	v_max3_f32 v223, v150, v151, v152
	v_max3_f32 v229, v166, v167, v168
	v_max3_f32 v217, v217, v221, v223
	v_max3_f32 v219, v219, v225, v229
	v_max3_f32 v221, v153, v154, v155
	v_max3_f32 v225, v169, v170, v171
	v_max3_f32 v223, v156, v157, v158
	v_max3_f32 v229, v172, v173, v174
	v_max3_f32 v221, v221, v223, v159
	v_max3_f32 v225, v225, v229, v175
	v_max_f32_e32 v217, v217, v221
	v_max_f32_e32 v219, v219, v225
	v_add_f32_e32 v221, v200, v217
	v_add_f32_e32 v225, v200, v219
	v_sub_f32_e32 v223, v221, v227
	v_sub_f32_e32 v229, v225, v215
	v_max_f32_e32 v223, v223, v229
	v_add_f32_e32 v223, 0x43080000, v223
	v_cmp_nlt_f32_e64 s[98:99], v223, 0
	s_nop 3
	s_cmp_eq_u64 s[98:99], 0
	s_cbranch_scc1 .Lat4_skip
	s_mov_b32 s51, 0
	s_branch .Lat4_redo
.Lat5_probe:
	ds_read_b128 v[160:163], v237 offset:40960
	ds_read_b128 v[164:167], v189
	ds_read_b128 v[202:205], v235 offset:40960
	ds_read_b128 v[244:247], v189 offset:4096
	ds_read_b128 v[248:251], v236 offset:40960
	ds_read_b128 v[252:255], v189 offset:1024
	s_waitcnt lgkmcnt(4)
	v_mfma_f32_32x32x16_bf16 v[144:159], v[160:163], v[164:167], v[128:143]
	s_waitcnt lgkmcnt(2)
	v_mfma_f32_32x32x16_bf16 v[160:175], v[202:205], v[244:247], v[128:143]
	ds_read_b128 v[202:205], v234 offset:40960
	ds_read_b128 v[244:247], v189 offset:5120
	v_add_u32_e32 v215, s40, v185
	v_add_u32_e32 v215, 0x60, v215
	v_cvt_f32_i32_e32 v215, v215
	v_add_f32_e32 v227, 0x41000000, v199
	v_mul_f32_e32 v200, v184, v215
	v_add_f32_e32 v215, 0x41000000, v201
	s_waitcnt lgkmcnt(2)
	v_mfma_f32_32x32x16_bf16 v[144:159], v[248:251], v[252:255], v[144:159]
	ds_read_b128 v[248:251], v241 offset:40960
	ds_read_b128 v[252:255], v189 offset:2048
	s_waitcnt lgkmcnt(2)
	v_mfma_f32_32x32x16_bf16 v[160:175], v[202:205], v[244:247], v[160:175]
	ds_read_b128 v[202:205], v239 offset:40960
	ds_read_b128 v[244:247], v189 offset:6144
	s_waitcnt lgkmcnt(2)
	v_mfma_f32_32x32x16_bf16 v[144:159], v[248:251], v[252:255], v[144:159]
	ds_read_b128 v[248:251], v240 offset:40960
	ds_read_b128 v[252:255], v189 offset:3072
	s_waitcnt lgkmcnt(2)
	v_mfma_f32_32x32x16_bf16 v[160:175], v[202:205], v[244:247], v[160:175]
	ds_read_b128 v[202:205], v238 offset:40960
	ds_read_b128 v[244:247], v189 offset:7168
	s_waitcnt lgkmcnt(2)
	v_mfma_f32_32x32x16_bf16 v[144:159], v[248:251], v[252:255], v[144:159]
	s_waitcnt lgkmcnt(0)
	v_mfma_f32_32x32x16_bf16 v[160:175], v[202:205], v[244:247], v[160:175]
	s_nop 7
	s_nop 7
	v_max3_f32 v217, v144, v145, v146
	v_max3_f32 v219, v160, v161, v162
	v_max3_f32 v221, v147, v148, v149
	v_max3_f32 v225, v163, v164, v165
	v_max3_f32 v223, v150, v151, v152
	v_max3_f32 v229, v166, v167, v168
	v_max3_f32 v217, v217, v221, v223
	v_max3_f32 v219, v219, v225, v229
	v_max3_f32 v221, v153, v154, v155
	v_max3_f32 v225, v169, v170, v171
	v_max3_f32 v223, v156, v157, v158
	v_max3_f32 v229, v172, v173, v174
	v_max3_f32 v221, v221, v223, v159
	v_max3_f32 v225, v225, v229, v175
	v_max_f32_e32 v217, v217, v221
	v_max_f32_e32 v219, v219, v225
	v_add_f32_e32 v221, v200, v217
	v_add_f32_e32 v225, v200, v219
	v_sub_f32_e32 v223, v221, v227
	v_sub_f32_e32 v229, v225, v215
	v_max_f32_e32 v223, v223, v229
	v_add_f32_e32 v223, 0x43080000, v223
	v_cmp_nlt_f32_e64 s[98:99], v223, 0
	s_nop 3
	s_cmp_eq_u64 s[98:99], 0
	s_cbranch_scc1 .Lat5_skip
	s_mov_b32 s51, 0
	s_branch .Lat5_redo
.Lat6_probe:
	ds_read_b128 v[160:163], v237 offset:32768
	ds_read_b128 v[164:167], v189
	ds_read_b128 v[202:205], v235 offset:32768
	ds_read_b128 v[244:247], v189 offset:4096
	ds_read_b128 v[248:251], v236 offset:32768
	ds_read_b128 v[252:255], v189 offset:1024
	s_waitcnt lgkmcnt(4)
	v_mfma_f32_32x32x16_bf16 v[144:159], v[160:163], v[164:167], v[128:143]
	s_waitcnt lgkmcnt(2)
	v_mfma_f32_32x32x16_bf16 v[160:175], v[202:205], v[244:247], v[128:143]
	ds_read_b128 v[202:205], v234 offset:32768
	ds_read_b128 v[244:247], v189 offset:5120
	v_add_u32_e32 v215, s40, v185
	v_add_u32_e32 v215, 0x40, v215
	v_cvt_f32_i32_e32 v215, v215
	v_add_f32_e32 v227, 0x41000000, v199
	v_mul_f32_e32 v200, v184, v215
	v_add_f32_e32 v215, 0x41000000, v201
	s_waitcnt lgkmcnt(2)
	v_mfma_f32_32x32x16_bf16 v[144:159], v[248:251], v[252:255], v[144:159]
	ds_read_b128 v[248:251], v241 offset:32768
	ds_read_b128 v[252:255], v189 offset:2048
	s_waitcnt lgkmcnt(2)
	v_mfma_f32_32x32x16_bf16 v[160:175], v[202:205], v[244:247], v[160:175]
	ds_read_b128 v[202:205], v239 offset:32768
	ds_read_b128 v[244:247], v189 offset:6144
	s_waitcnt lgkmcnt(2)
	v_mfma_f32_32x32x16_bf16 v[144:159], v[248:251], v[252:255], v[144:159]
	ds_read_b128 v[248:251], v240 offset:32768
	ds_read_b128 v[252:255], v189 offset:3072
	s_waitcnt lgkmcnt(2)
	v_mfma_f32_32x32x16_bf16 v[160:175], v[202:205], v[244:247], v[160:175]
	ds_read_b128 v[202:205], v238 offset:32768
	ds_read_b128 v[244:247], v189 offset:7168
	s_waitcnt lgkmcnt(2)
	v_mfma_f32_32x32x16_bf16 v[144:159], v[248:251], v[252:255], v[144:159]
	s_waitcnt lgkmcnt(0)
	v_mfma_f32_32x32x16_bf16 v[160:175], v[202:205], v[244:247], v[160:175]
	s_nop 7
	s_nop 7
	v_max3_f32 v217, v144, v145, v146
	v_max3_f32 v219, v160, v161, v162
	v_max3_f32 v221, v147, v148, v149
	v_max3_f32 v225, v163, v164, v165
	v_max3_f32 v223, v150, v151, v152
	v_max3_f32 v229, v166, v167, v168
	v_max3_f32 v217, v217, v221, v223
	v_max3_f32 v219, v219, v225, v229
	v_max3_f32 v221, v153, v154, v155
	v_max3_f32 v225, v169, v170, v171
	v_max3_f32 v223, v156, v157, v158
	v_max3_f32 v229, v172, v173, v174
	v_max3_f32 v221, v221, v223, v159
	v_max3_f32 v225, v225, v229, v175
	v_max_f32_e32 v217, v217, v221
	v_max_f32_e32 v219, v219, v225
	v_add_f32_e32 v221, v200, v217
	v_add_f32_e32 v225, v200, v219
	v_sub_f32_e32 v223, v221, v227
	v_sub_f32_e32 v229, v225, v215
	v_max_f32_e32 v223, v223, v229
	v_add_f32_e32 v223, 0x43080000, v223
	v_cmp_nlt_f32_e64 s[98:99], v223, 0
	s_nop 3
	s_cmp_eq_u64 s[98:99], 0
	s_cbranch_scc1 .Lat6_skip
	s_mov_b32 s51, 0
	s_branch .Lat6_redo
